# conv LayerNorm wave_sum: ds_bpermute xor-butterfly replaced by DPP quad_perm/row_mirror + v_permlane16/32_swap (bit-identical sums, no LDS round trips)
# speedup vs baseline: 1.0086x; 1.0086x over previous
.LBB0_722:
	s_or_b64 exec, exec, s[4:5]
	v_readlane_b32 s4, v239, 1
	v_and_b32_e32 v74, 0x3fc, v100
	v_readlane_b32 s16, v239, 13
	v_readlane_b32 s17, v239, 14
	s_waitcnt lgkmcnt(0)
	s_barrier
	s_waitcnt vmcnt(0)
	v_lshl_add_u64 v[66:67], s[16:17], 0, v[74:75]
	v_add_co_u32_e32 v68, vcc, 0x1000, v66
	s_nop 1
	v_addc_co_u32_e32 v69, vcc, 0, v67, vcc
	v_add_co_u32_e32 v70, vcc, 0x2000, v66
	v_readlane_b32 s18, v239, 15
	s_nop 0
	v_addc_co_u32_e32 v71, vcc, 0, v67, vcc
	global_load_dword v123, v[68:69], off
	global_load_dword v122, v[68:69], off offset:1024
	global_load_dword v120, v[68:69], off offset:2048
	global_load_dword v118, v[68:69], off offset:3072
	global_load_dword v121, v[70:71], off
	global_load_dword v119, v[70:71], off offset:1024
	global_load_dword v117, v[70:71], off offset:2048
	global_load_dword v116, v[70:71], off offset:3072
	v_add_co_u32_e32 v68, vcc, 0x3000, v66
	v_readlane_b32 s19, v239, 16
	s_nop 0
	v_addc_co_u32_e32 v69, vcc, 0, v67, vcc
	v_add_co_u32_e32 v70, vcc, s27, v66
	v_readlane_b32 s5, v239, 2
	s_nop 0
	v_addc_co_u32_e32 v71, vcc, 0, v67, vcc
	global_load_dword v128, v74, s[16:17]
	global_load_dword v127, v74, s[16:17] offset:1024
	global_load_dword v126, v74, s[16:17] offset:2048
	global_load_dword v125, v74, s[16:17] offset:3072
	global_load_dword v124, v74, s[18:19]
	global_load_dword v147, v[68:69], off
	global_load_dword v146, v[68:69], off offset:1024
	global_load_dword v144, v[68:69], off offset:2048
	global_load_dword v142, v[68:69], off offset:3072
	global_load_dword v140, v[70:71], off
	global_load_dword v138, v[70:71], off offset:1024
	global_load_dword v136, v[70:71], off offset:2048
	global_load_dword v133, v[70:71], off offset:3072
	v_add_co_u32_e32 v68, vcc, 0x5000, v66
	v_readlane_b32 s6, v239, 3
	s_nop 0
	v_addc_co_u32_e32 v69, vcc, 0, v67, vcc
	v_add_co_u32_e32 v70, vcc, 0x6000, v66
	v_readlane_b32 s7, v239, 4
	s_nop 0
	v_addc_co_u32_e32 v71, vcc, 0, v67, vcc
	global_load_dword v145, v[68:69], off
	global_load_dword v143, v[68:69], off offset:1024
	global_load_dword v141, v[68:69], off offset:2048
	global_load_dword v139, v[68:69], off offset:3072
	global_load_dword v137, v[70:71], off
	global_load_dword v134, v[70:71], off offset:1024
	global_load_dword v131, v[70:71], off offset:2048
	global_load_dword v129, v[70:71], off offset:3072
	v_add_co_u32_e32 v66, vcc, 0x7000, v66
	v_readlane_b32 s8, v239, 5
	s_nop 0
	v_addc_co_u32_e32 v67, vcc, 0, v67, vcc
	global_load_dword v135, v[66:67], off
	global_load_dword v132, v[66:67], off offset:1024
	global_load_dword v130, v[66:67], off offset:2048
	v_lshlrev_b32_e32 v66, 6, v114
	v_and_b32_e32 v152, 0xffffc000, v66
	v_add3_u32 v66, 0, v152, v74
	ds_read2st64_b32 v[148:149], v66 offset1:4
	ds_read2st64_b32 v[150:151], v66 offset0:8 offset1:12
	ds_read2st64_b32 v[108:109], v66 offset0:16 offset1:20
	ds_read2st64_b32 v[106:107], v66 offset0:24 offset1:28
	ds_read2st64_b32 v[104:105], v66 offset0:32 offset1:36
	ds_read2st64_b32 v[102:103], v66 offset0:40 offset1:44
	ds_read2st64_b32 v[100:101], v66 offset0:48 offset1:52
	ds_read2st64_b32 v[98:99], v66 offset0:56 offset1:60
	ds_read2st64_b32 v[96:97], v66 offset0:64 offset1:68
	ds_read2st64_b32 v[94:95], v66 offset0:72 offset1:76
	ds_read2st64_b32 v[92:93], v66 offset0:80 offset1:84
	ds_read2st64_b32 v[90:91], v66 offset0:88 offset1:92
	ds_read2st64_b32 v[88:89], v66 offset0:96 offset1:100
	ds_read2st64_b32 v[86:87], v66 offset0:104 offset1:108
	ds_read2st64_b32 v[84:85], v66 offset0:112 offset1:116
	ds_read2st64_b32 v[82:83], v66 offset0:120 offset1:124
	ds_read2st64_b32 v[80:81], v66 offset0:128 offset1:132
	ds_read2st64_b32 v[78:79], v66 offset0:136 offset1:140
	ds_read2st64_b32 v[76:77], v66 offset0:144 offset1:148
	ds_read2st64_b32 v[72:73], v66 offset0:152 offset1:156
	ds_read2st64_b32 v[70:71], v66 offset0:160 offset1:164
	ds_read2st64_b32 v[68:69], v66 offset0:168 offset1:172
	ds_read2st64_b32 v[66:67], v66 offset0:176 offset1:180
	v_add3_u32 v74, s34, v152, v74
	v_readlane_b32 s9, v239, 6
	v_readlane_b32 s10, v239, 7
	v_readlane_b32 s11, v239, 8
	v_readlane_b32 s12, v239, 9
	v_readlane_b32 s13, v239, 10
	v_readlane_b32 s14, v239, 11
	v_readlane_b32 s15, v239, 12
	v_readlane_b32 s4, v239, 49
	v_readlane_b32 s5, v239, 50
	v_readlane_b32 s6, v239, 51
	v_readlane_b32 s7, v239, 52
	v_readlane_b32 s10, v239, 55
	v_readlane_b32 s11, v239, 56
	s_add_i32 s41, s41, s42
	s_add_i32 s40, s40, s68
	s_add_i32 s3, s3, s26
	s_cmpk_lt_i32 s40, 0x410
	v_readlane_b32 s8, v239, 53
	v_readlane_b32 s9, v239, 54
	v_readlane_b32 s12, v239, 57
	v_readlane_b32 s13, v239, 58
	v_readlane_b32 s14, v239, 59
	v_readlane_b32 s15, v239, 60
	v_readlane_b32 s16, v239, 61
	v_readlane_b32 s17, v239, 62
	v_readlane_b32 s18, v239, 63
	v_readlane_b32 s19, v238, 0
	s_waitcnt vmcnt(19) lgkmcnt(14)
	v_fma_f32 v148, v128, v148, v124
	v_fmac_f32_e32 v148, v127, v149
	v_fma_f32 v149, v128, v149, v124
	v_fmac_f32_e32 v149, v127, v150
	v_fmac_f32_e32 v148, v126, v150
	v_fmac_f32_e32 v149, v126, v151
	v_fmac_f32_e32 v148, v125, v151
	v_fmac_f32_e32 v149, v125, v108
	v_fmac_f32_e32 v148, v123, v108
	v_fmac_f32_e32 v149, v123, v109
	v_fmac_f32_e32 v148, v122, v109
	v_fmac_f32_e32 v149, v122, v106
	v_fmac_f32_e32 v148, v120, v106
	v_fmac_f32_e32 v149, v120, v107
	v_fmac_f32_e32 v148, v118, v107
	v_fmac_f32_e32 v149, v118, v104
	v_fmac_f32_e32 v148, v121, v104
	v_fmac_f32_e32 v149, v121, v105
	v_fmac_f32_e32 v148, v119, v105
	v_fmac_f32_e32 v149, v119, v102
	v_fmac_f32_e32 v148, v117, v102
	v_fmac_f32_e32 v149, v117, v103
	v_fmac_f32_e32 v148, v116, v103
	v_fmac_f32_e32 v149, v116, v100
	s_waitcnt vmcnt(18)
	v_fmac_f32_e32 v148, v147, v100
	v_fmac_f32_e32 v149, v147, v101
	s_waitcnt vmcnt(17)
	v_fmac_f32_e32 v148, v146, v101
	v_fmac_f32_e32 v149, v146, v98
	s_waitcnt vmcnt(16)
	v_fmac_f32_e32 v148, v144, v98
	v_fmac_f32_e32 v149, v144, v99
	s_waitcnt vmcnt(15)
	v_fmac_f32_e32 v148, v142, v99
	v_fmac_f32_e32 v149, v142, v96
	s_waitcnt vmcnt(14)
	v_fmac_f32_e32 v148, v140, v96
	v_fmac_f32_e32 v149, v140, v97
	s_waitcnt vmcnt(13)
	v_fmac_f32_e32 v148, v138, v97
	s_waitcnt lgkmcnt(13)
	v_fmac_f32_e32 v149, v138, v94
	s_waitcnt vmcnt(12)
	v_fmac_f32_e32 v148, v136, v94
	v_fmac_f32_e32 v149, v136, v95
	s_waitcnt vmcnt(11)
	v_fmac_f32_e32 v148, v133, v95
	s_waitcnt lgkmcnt(12)
	v_fmac_f32_e32 v149, v133, v92
	s_waitcnt vmcnt(10)
	v_fmac_f32_e32 v148, v145, v92
	v_fmac_f32_e32 v149, v145, v93
	s_waitcnt vmcnt(9)
	v_fmac_f32_e32 v148, v143, v93
	s_waitcnt lgkmcnt(11)
	v_fmac_f32_e32 v149, v143, v90
	s_waitcnt vmcnt(8)
	v_fmac_f32_e32 v148, v141, v90
	v_fmac_f32_e32 v149, v141, v91
	s_waitcnt vmcnt(7)
	v_fmac_f32_e32 v148, v139, v91
	s_waitcnt lgkmcnt(10)
	v_fmac_f32_e32 v149, v139, v88
	s_waitcnt vmcnt(6)
	v_fmac_f32_e32 v148, v137, v88
	v_fmac_f32_e32 v149, v137, v89
	s_waitcnt vmcnt(5)
	v_fmac_f32_e32 v148, v134, v89
	s_waitcnt lgkmcnt(9)
	v_fmac_f32_e32 v149, v134, v86
	s_waitcnt vmcnt(4)
	v_fmac_f32_e32 v148, v131, v86
	v_fmac_f32_e32 v149, v131, v87
	s_waitcnt vmcnt(3)
	v_fmac_f32_e32 v148, v129, v87
	s_waitcnt lgkmcnt(8)
	v_fmac_f32_e32 v149, v129, v84
	s_waitcnt vmcnt(2)
	v_fmac_f32_e32 v148, v135, v84
	v_fmac_f32_e32 v149, v135, v85
	s_waitcnt vmcnt(1)
	v_fmac_f32_e32 v148, v132, v85
	s_waitcnt lgkmcnt(7)
	v_fmac_f32_e32 v149, v132, v82
	s_waitcnt vmcnt(0)
	v_fmac_f32_e32 v148, v130, v82
	v_fmac_f32_e32 v149, v130, v83
	ds_write2st64_b32 v74, v148, v149 offset1:4
	v_fma_f32 v148, v128, v150, v124
	v_fmac_f32_e32 v148, v127, v151
	v_fma_f32 v149, v128, v151, v124
	v_fmac_f32_e32 v148, v126, v108
	v_fmac_f32_e32 v149, v127, v108
	v_fma_f32 v108, v128, v108, v124
	v_fmac_f32_e32 v148, v125, v109
	v_fmac_f32_e32 v149, v126, v109
	v_fmac_f32_e32 v108, v127, v109
	v_fma_f32 v109, v128, v109, v124
	v_fmac_f32_e32 v148, v123, v106
	v_fmac_f32_e32 v149, v125, v106
	v_fmac_f32_e32 v108, v126, v106
	v_fmac_f32_e32 v109, v127, v106
	v_fma_f32 v106, v128, v106, v124
	v_fmac_f32_e32 v148, v122, v107
	v_fmac_f32_e32 v149, v123, v107
	v_fmac_f32_e32 v108, v125, v107
	v_fmac_f32_e32 v109, v126, v107
	v_fmac_f32_e32 v106, v127, v107
	v_fma_f32 v107, v128, v107, v124
	v_fmac_f32_e32 v148, v120, v104
	v_fmac_f32_e32 v149, v122, v104
	v_fmac_f32_e32 v108, v123, v104
	v_fmac_f32_e32 v109, v125, v104
	v_fmac_f32_e32 v106, v126, v104
	v_fmac_f32_e32 v107, v127, v104
	v_fma_f32 v104, v128, v104, v124
	v_fmac_f32_e32 v148, v118, v105
	v_fmac_f32_e32 v149, v120, v105
	v_fmac_f32_e32 v108, v122, v105
	v_fmac_f32_e32 v109, v123, v105
	v_fmac_f32_e32 v106, v125, v105
	v_fmac_f32_e32 v107, v126, v105
	v_fmac_f32_e32 v104, v127, v105
	v_fma_f32 v105, v128, v105, v124
	v_fmac_f32_e32 v148, v121, v102
	v_fmac_f32_e32 v149, v118, v102
	v_fmac_f32_e32 v108, v120, v102
	v_fmac_f32_e32 v109, v122, v102
	v_fmac_f32_e32 v106, v123, v102
	v_fmac_f32_e32 v107, v125, v102
	v_fmac_f32_e32 v104, v126, v102
	v_fmac_f32_e32 v105, v127, v102
	v_fma_f32 v102, v128, v102, v124
	v_fmac_f32_e32 v148, v119, v103
	v_fmac_f32_e32 v149, v121, v103
	v_fmac_f32_e32 v108, v118, v103
	v_fmac_f32_e32 v109, v120, v103
	v_fmac_f32_e32 v106, v122, v103
	v_fmac_f32_e32 v107, v123, v103
	v_fmac_f32_e32 v104, v125, v103
	v_fmac_f32_e32 v105, v126, v103
	v_fmac_f32_e32 v102, v127, v103
	v_fma_f32 v103, v128, v103, v124
	v_fmac_f32_e32 v148, v117, v100
	v_fmac_f32_e32 v149, v119, v100
	v_fmac_f32_e32 v108, v121, v100
	v_fmac_f32_e32 v109, v118, v100
	v_fmac_f32_e32 v106, v120, v100
	v_fmac_f32_e32 v107, v122, v100
	v_fmac_f32_e32 v104, v123, v100
	v_fmac_f32_e32 v105, v125, v100
	v_fmac_f32_e32 v102, v126, v100
	v_fmac_f32_e32 v103, v127, v100
	v_fma_f32 v100, v128, v100, v124
	v_fmac_f32_e32 v148, v116, v101
	v_fmac_f32_e32 v149, v117, v101
	v_fmac_f32_e32 v108, v119, v101
	v_fmac_f32_e32 v109, v121, v101
	v_fmac_f32_e32 v106, v118, v101
	v_fmac_f32_e32 v107, v120, v101
	v_fmac_f32_e32 v104, v122, v101
	v_fmac_f32_e32 v105, v123, v101
	v_fmac_f32_e32 v102, v125, v101
	v_fmac_f32_e32 v103, v126, v101
	v_fmac_f32_e32 v100, v127, v101
	v_fma_f32 v101, v128, v101, v124
	v_fmac_f32_e32 v148, v147, v98
	v_fmac_f32_e32 v149, v116, v98
	v_fmac_f32_e32 v108, v117, v98
	v_fmac_f32_e32 v109, v119, v98
	v_fmac_f32_e32 v106, v121, v98
	v_fmac_f32_e32 v107, v118, v98
	v_fmac_f32_e32 v104, v120, v98
	v_fmac_f32_e32 v105, v122, v98
	v_fmac_f32_e32 v102, v123, v98
	v_fmac_f32_e32 v103, v125, v98
	v_fmac_f32_e32 v100, v126, v98
	v_fmac_f32_e32 v101, v127, v98
	v_fma_f32 v98, v128, v98, v124
	v_fmac_f32_e32 v124, v128, v99
	v_fmac_f32_e32 v98, v127, v99
	v_fmac_f32_e32 v124, v127, v96
	v_fmac_f32_e32 v101, v126, v99
	v_fmac_f32_e32 v98, v126, v96
	v_fmac_f32_e32 v124, v126, v97
	v_fmac_f32_e32 v100, v125, v99
	v_fmac_f32_e32 v101, v125, v96
	v_fmac_f32_e32 v98, v125, v97
	v_fmac_f32_e32 v124, v125, v94
	v_fmac_f32_e32 v103, v123, v99
	v_fmac_f32_e32 v100, v123, v96
	v_fmac_f32_e32 v101, v123, v97
	v_fmac_f32_e32 v98, v123, v94
	v_fmac_f32_e32 v124, v123, v95
	v_fmac_f32_e32 v102, v122, v99
	v_fmac_f32_e32 v103, v122, v96
	v_fmac_f32_e32 v100, v122, v97
	v_fmac_f32_e32 v101, v122, v94
	v_fmac_f32_e32 v98, v122, v95
	v_fmac_f32_e32 v124, v122, v92
	v_fmac_f32_e32 v105, v120, v99
	v_fmac_f32_e32 v102, v120, v96
	v_fmac_f32_e32 v103, v120, v97
	v_fmac_f32_e32 v100, v120, v94
	v_fmac_f32_e32 v101, v120, v95
	v_fmac_f32_e32 v98, v120, v92
	v_fmac_f32_e32 v124, v120, v93
	v_fmac_f32_e32 v104, v118, v99
	v_fmac_f32_e32 v105, v118, v96
	v_fmac_f32_e32 v102, v118, v97
	v_fmac_f32_e32 v103, v118, v94
	v_fmac_f32_e32 v100, v118, v95
	v_fmac_f32_e32 v101, v118, v92
	v_fmac_f32_e32 v98, v118, v93
	v_fmac_f32_e32 v124, v118, v90
	v_fmac_f32_e32 v107, v121, v99
	v_fmac_f32_e32 v104, v121, v96
	v_fmac_f32_e32 v105, v121, v97
	v_fmac_f32_e32 v102, v121, v94
	v_fmac_f32_e32 v103, v121, v95
	v_fmac_f32_e32 v100, v121, v92
	v_fmac_f32_e32 v101, v121, v93
	v_fmac_f32_e32 v98, v121, v90
	v_fmac_f32_e32 v124, v121, v91
	v_fmac_f32_e32 v106, v119, v99
	v_fmac_f32_e32 v107, v119, v96
	v_fmac_f32_e32 v104, v119, v97
	v_fmac_f32_e32 v105, v119, v94
	v_fmac_f32_e32 v102, v119, v95
	v_fmac_f32_e32 v103, v119, v92
	v_fmac_f32_e32 v100, v119, v93
	v_fmac_f32_e32 v101, v119, v90
	v_fmac_f32_e32 v98, v119, v91
	v_fmac_f32_e32 v124, v119, v88
	v_fmac_f32_e32 v109, v117, v99
	v_fmac_f32_e32 v106, v117, v96
	v_fmac_f32_e32 v107, v117, v97
	v_fmac_f32_e32 v104, v117, v94
	v_fmac_f32_e32 v105, v117, v95
	v_fmac_f32_e32 v102, v117, v92
	v_fmac_f32_e32 v103, v117, v93
	v_fmac_f32_e32 v100, v117, v90
	v_fmac_f32_e32 v101, v117, v91
	v_fmac_f32_e32 v98, v117, v88
	v_fmac_f32_e32 v124, v117, v89
	v_fmac_f32_e32 v108, v116, v99
	v_fmac_f32_e32 v109, v116, v96
	v_fmac_f32_e32 v106, v116, v97
	v_fmac_f32_e32 v107, v116, v94
	v_fmac_f32_e32 v104, v116, v95
	v_fmac_f32_e32 v105, v116, v92
	v_fmac_f32_e32 v102, v116, v93
	v_fmac_f32_e32 v103, v116, v90
	v_fmac_f32_e32 v100, v116, v91
	v_fmac_f32_e32 v101, v116, v88
	v_fmac_f32_e32 v98, v116, v89
	v_fmac_f32_e32 v124, v116, v86
	v_fmac_f32_e32 v149, v147, v99
	v_fmac_f32_e32 v108, v147, v96
	v_fmac_f32_e32 v109, v147, v97
	v_fmac_f32_e32 v106, v147, v94
	v_fmac_f32_e32 v107, v147, v95
	v_fmac_f32_e32 v104, v147, v92
	v_fmac_f32_e32 v105, v147, v93
	v_fmac_f32_e32 v102, v147, v90
	v_fmac_f32_e32 v103, v147, v91
	v_fmac_f32_e32 v100, v147, v88
	v_fmac_f32_e32 v101, v147, v89
	v_fmac_f32_e32 v98, v147, v86
	v_fmac_f32_e32 v124, v147, v87
	v_fmac_f32_e32 v148, v146, v99
	v_fmac_f32_e32 v149, v146, v96
	v_fmac_f32_e32 v108, v146, v97
	v_fmac_f32_e32 v109, v146, v94
	v_fmac_f32_e32 v106, v146, v95
	v_fmac_f32_e32 v107, v146, v92
	v_fmac_f32_e32 v104, v146, v93
	v_fmac_f32_e32 v105, v146, v90
	v_fmac_f32_e32 v102, v146, v91
	v_fmac_f32_e32 v103, v146, v88
	v_fmac_f32_e32 v100, v146, v89
	v_fmac_f32_e32 v101, v146, v86
	v_fmac_f32_e32 v98, v146, v87
	v_fmac_f32_e32 v124, v146, v84
	v_fmac_f32_e32 v148, v144, v96
	v_fmac_f32_e32 v149, v144, v97
	v_fmac_f32_e32 v108, v144, v94
	v_fmac_f32_e32 v109, v144, v95
	v_fmac_f32_e32 v106, v144, v92
	v_fmac_f32_e32 v107, v144, v93
	v_fmac_f32_e32 v104, v144, v90
	v_fmac_f32_e32 v105, v144, v91
	v_fmac_f32_e32 v102, v144, v88
	v_fmac_f32_e32 v103, v144, v89
	v_fmac_f32_e32 v100, v144, v86
	v_fmac_f32_e32 v101, v144, v87
	v_fmac_f32_e32 v98, v144, v84
	v_fmac_f32_e32 v124, v144, v85
	v_fmac_f32_e32 v148, v142, v97
	v_fmac_f32_e32 v149, v142, v94
	v_fmac_f32_e32 v108, v142, v95
	v_fmac_f32_e32 v109, v142, v92
	v_fmac_f32_e32 v106, v142, v93
	v_fmac_f32_e32 v107, v142, v90
	v_fmac_f32_e32 v104, v142, v91
	v_fmac_f32_e32 v105, v142, v88
	v_fmac_f32_e32 v102, v142, v89
	v_fmac_f32_e32 v103, v142, v86
	v_fmac_f32_e32 v100, v142, v87
	v_fmac_f32_e32 v101, v142, v84
	v_fmac_f32_e32 v98, v142, v85
	v_fmac_f32_e32 v124, v142, v82
	v_fmac_f32_e32 v148, v140, v94
	v_fmac_f32_e32 v149, v140, v95
	v_fmac_f32_e32 v108, v140, v92
	v_fmac_f32_e32 v109, v140, v93
	v_fmac_f32_e32 v106, v140, v90
	v_fmac_f32_e32 v107, v140, v91
	v_fmac_f32_e32 v104, v140, v88
	v_fmac_f32_e32 v105, v140, v89
	v_fmac_f32_e32 v102, v140, v86
	v_fmac_f32_e32 v103, v140, v87
	v_fmac_f32_e32 v100, v140, v84
	v_fmac_f32_e32 v101, v140, v85
	v_fmac_f32_e32 v98, v140, v82
	v_fmac_f32_e32 v124, v140, v83
	v_fmac_f32_e32 v148, v138, v95
	v_fmac_f32_e32 v149, v138, v92
	v_fmac_f32_e32 v108, v138, v93
	v_fmac_f32_e32 v109, v138, v90
	v_fmac_f32_e32 v106, v138, v91
	v_fmac_f32_e32 v107, v138, v88
	v_fmac_f32_e32 v104, v138, v89
	v_fmac_f32_e32 v105, v138, v86
	v_fmac_f32_e32 v102, v138, v87
	v_fmac_f32_e32 v103, v138, v84
	v_fmac_f32_e32 v100, v138, v85
	v_fmac_f32_e32 v101, v138, v82
	v_fmac_f32_e32 v98, v138, v83
	s_waitcnt lgkmcnt(7)
	v_fmac_f32_e32 v124, v138, v80
	v_fmac_f32_e32 v148, v136, v92
	v_fmac_f32_e32 v149, v136, v93
	v_fmac_f32_e32 v108, v136, v90
	v_fmac_f32_e32 v109, v136, v91
	v_fmac_f32_e32 v106, v136, v88
	v_fmac_f32_e32 v107, v136, v89
	v_fmac_f32_e32 v104, v136, v86
	v_fmac_f32_e32 v105, v136, v87
	v_fmac_f32_e32 v102, v136, v84
	v_fmac_f32_e32 v103, v136, v85
	v_fmac_f32_e32 v100, v136, v82
	v_fmac_f32_e32 v101, v136, v83
	v_fmac_f32_e32 v98, v136, v80
	v_fmac_f32_e32 v124, v136, v81
	v_fmac_f32_e32 v148, v133, v93
	v_fmac_f32_e32 v149, v133, v90
	v_fmac_f32_e32 v108, v133, v91
	v_fmac_f32_e32 v109, v133, v88
	v_fmac_f32_e32 v106, v133, v89
	v_fmac_f32_e32 v107, v133, v86
	v_fmac_f32_e32 v104, v133, v87
	v_fmac_f32_e32 v105, v133, v84
	v_fmac_f32_e32 v102, v133, v85
	v_fmac_f32_e32 v103, v133, v82
	v_fmac_f32_e32 v100, v133, v83
	v_fmac_f32_e32 v101, v133, v80
	v_fmac_f32_e32 v98, v133, v81
	s_waitcnt lgkmcnt(6)
	v_fmac_f32_e32 v124, v133, v78
	v_fmac_f32_e32 v148, v145, v90
	v_fmac_f32_e32 v149, v145, v91
	v_fmac_f32_e32 v108, v145, v88
	v_fmac_f32_e32 v109, v145, v89
	v_fmac_f32_e32 v106, v145, v86
	v_fmac_f32_e32 v107, v145, v87
	v_fmac_f32_e32 v104, v145, v84
	v_fmac_f32_e32 v105, v145, v85
	v_fmac_f32_e32 v102, v145, v82
	v_fmac_f32_e32 v103, v145, v83
	v_fmac_f32_e32 v100, v145, v80
	v_fmac_f32_e32 v101, v145, v81
	v_fmac_f32_e32 v98, v145, v78
	v_fmac_f32_e32 v124, v145, v79
	v_fmac_f32_e32 v148, v143, v91
	v_fmac_f32_e32 v149, v143, v88
	v_fmac_f32_e32 v108, v143, v89
	v_fmac_f32_e32 v109, v143, v86
	v_fmac_f32_e32 v106, v143, v87
	v_fmac_f32_e32 v107, v143, v84
	v_fmac_f32_e32 v104, v143, v85
	v_fmac_f32_e32 v105, v143, v82
	v_fmac_f32_e32 v102, v143, v83
	v_fmac_f32_e32 v103, v143, v80
	v_fmac_f32_e32 v100, v143, v81
	v_fmac_f32_e32 v101, v143, v78
	v_fmac_f32_e32 v98, v143, v79
	s_waitcnt lgkmcnt(5)
	v_fmac_f32_e32 v124, v143, v76
	v_fmac_f32_e32 v148, v141, v88
	v_fmac_f32_e32 v149, v141, v89
	v_fmac_f32_e32 v108, v141, v86
	v_fmac_f32_e32 v109, v141, v87
	v_fmac_f32_e32 v106, v141, v84
	v_fmac_f32_e32 v107, v141, v85
	v_fmac_f32_e32 v104, v141, v82
	v_fmac_f32_e32 v105, v141, v83
	v_fmac_f32_e32 v102, v141, v80
	v_fmac_f32_e32 v103, v141, v81
	v_fmac_f32_e32 v100, v141, v78
	v_fmac_f32_e32 v101, v141, v79
	v_fmac_f32_e32 v98, v141, v76
	v_fmac_f32_e32 v124, v141, v77
	v_fmac_f32_e32 v148, v139, v89
	v_fmac_f32_e32 v149, v139, v86
	v_fmac_f32_e32 v108, v139, v87
	v_fmac_f32_e32 v109, v139, v84
	v_fmac_f32_e32 v106, v139, v85
	v_fmac_f32_e32 v107, v139, v82
	v_fmac_f32_e32 v104, v139, v83
	v_fmac_f32_e32 v105, v139, v80
	v_fmac_f32_e32 v102, v139, v81
	v_fmac_f32_e32 v103, v139, v78
	v_fmac_f32_e32 v100, v139, v79
	v_fmac_f32_e32 v101, v139, v76
	v_fmac_f32_e32 v98, v139, v77
	s_waitcnt lgkmcnt(4)
	v_fmac_f32_e32 v124, v139, v72
	v_fmac_f32_e32 v148, v137, v86
	v_fmac_f32_e32 v149, v137, v87
	v_fmac_f32_e32 v108, v137, v84
	v_fmac_f32_e32 v109, v137, v85
	v_fmac_f32_e32 v106, v137, v82
	v_fmac_f32_e32 v107, v137, v83
	v_fmac_f32_e32 v104, v137, v80
	v_fmac_f32_e32 v105, v137, v81
	v_fmac_f32_e32 v102, v137, v78
	v_fmac_f32_e32 v103, v137, v79
	v_fmac_f32_e32 v100, v137, v76
	v_fmac_f32_e32 v101, v137, v77
	v_fmac_f32_e32 v98, v137, v72
	v_fmac_f32_e32 v124, v137, v73
	v_fmac_f32_e32 v148, v134, v87
	v_fmac_f32_e32 v149, v134, v84
	v_fmac_f32_e32 v108, v134, v85
	v_fmac_f32_e32 v109, v134, v82
	v_fmac_f32_e32 v106, v134, v83
	v_fmac_f32_e32 v107, v134, v80
	v_fmac_f32_e32 v104, v134, v81
	v_fmac_f32_e32 v105, v134, v78
	v_fmac_f32_e32 v102, v134, v79
	v_fmac_f32_e32 v103, v134, v76
	v_fmac_f32_e32 v100, v134, v77
	v_fmac_f32_e32 v101, v134, v72
	v_fmac_f32_e32 v98, v134, v73
	s_waitcnt lgkmcnt(3)
	v_fmac_f32_e32 v124, v134, v70
	v_fmac_f32_e32 v148, v131, v84
	v_fmac_f32_e32 v149, v131, v85
	v_fmac_f32_e32 v108, v131, v82
	v_fmac_f32_e32 v109, v131, v83
	v_fmac_f32_e32 v106, v131, v80
	v_fmac_f32_e32 v107, v131, v81
	v_fmac_f32_e32 v104, v131, v78
	v_fmac_f32_e32 v105, v131, v79
	v_fmac_f32_e32 v102, v131, v76
	v_fmac_f32_e32 v103, v131, v77
	v_fmac_f32_e32 v100, v131, v72
	v_fmac_f32_e32 v101, v131, v73
	v_fmac_f32_e32 v98, v131, v70
	v_fmac_f32_e32 v124, v131, v71
	v_fmac_f32_e32 v148, v129, v85
	v_fmac_f32_e32 v149, v129, v82
	v_fmac_f32_e32 v108, v129, v83
	v_fmac_f32_e32 v109, v129, v80
	v_fmac_f32_e32 v106, v129, v81
	v_fmac_f32_e32 v107, v129, v78
	v_fmac_f32_e32 v104, v129, v79
	v_fmac_f32_e32 v105, v129, v76
	v_fmac_f32_e32 v102, v129, v77
	v_fmac_f32_e32 v103, v129, v72
	v_fmac_f32_e32 v100, v129, v73
	v_fmac_f32_e32 v101, v129, v70
	v_fmac_f32_e32 v98, v129, v71
	s_waitcnt lgkmcnt(2)
	v_fmac_f32_e32 v124, v129, v68
	v_fmac_f32_e32 v148, v135, v82
	v_fmac_f32_e32 v149, v135, v83
	v_fmac_f32_e32 v108, v135, v80
	v_fmac_f32_e32 v109, v135, v81
	v_fmac_f32_e32 v106, v135, v78
	v_fmac_f32_e32 v107, v135, v79
	v_fmac_f32_e32 v104, v135, v76
	v_fmac_f32_e32 v105, v135, v77
	v_fmac_f32_e32 v102, v135, v72
	v_fmac_f32_e32 v103, v135, v73
	v_fmac_f32_e32 v100, v135, v70
	v_fmac_f32_e32 v101, v135, v71
	v_fmac_f32_e32 v98, v135, v68
	v_fmac_f32_e32 v124, v135, v69
	v_fmac_f32_e32 v148, v132, v83
	v_fmac_f32_e32 v149, v132, v80
	v_fmac_f32_e32 v108, v132, v81
	v_fmac_f32_e32 v109, v132, v78
	v_fmac_f32_e32 v106, v132, v79
	v_fmac_f32_e32 v107, v132, v76
	v_fmac_f32_e32 v104, v132, v77
	v_fmac_f32_e32 v105, v132, v72
	v_fmac_f32_e32 v102, v132, v73
	v_fmac_f32_e32 v103, v132, v70
	v_fmac_f32_e32 v100, v132, v71
	v_fmac_f32_e32 v101, v132, v68
	v_fmac_f32_e32 v98, v132, v69
	s_waitcnt lgkmcnt(1)
	v_fmac_f32_e32 v124, v132, v66
	v_fmac_f32_e32 v148, v130, v80
	v_fmac_f32_e32 v149, v130, v81
	v_fmac_f32_e32 v108, v130, v78
	v_fmac_f32_e32 v109, v130, v79
	v_fmac_f32_e32 v106, v130, v76
	v_fmac_f32_e32 v107, v130, v77
	v_fmac_f32_e32 v104, v130, v72
	v_fmac_f32_e32 v105, v130, v73
	v_fmac_f32_e32 v102, v130, v70
	v_fmac_f32_e32 v103, v130, v71
	v_fmac_f32_e32 v100, v130, v68
	v_fmac_f32_e32 v101, v130, v69
	v_fmac_f32_e32 v98, v130, v66
	v_fmac_f32_e32 v124, v130, v67
	ds_write2st64_b32 v74, v148, v149 offset0:8 offset1:12
	ds_write2st64_b32 v74, v108, v109 offset0:16 offset1:20
	ds_write2st64_b32 v74, v106, v107 offset0:24 offset1:28
	ds_write2st64_b32 v74, v104, v105 offset0:32 offset1:36
	ds_write2st64_b32 v74, v102, v103 offset0:40 offset1:44
	ds_write2st64_b32 v74, v100, v101 offset0:48 offset1:52
	ds_write2st64_b32 v74, v98, v124 offset0:56 offset1:60
	v_lshlrev_b32_e32 v74, 2, v115
	v_add_u32_e32 v86, s34, v74
	v_lshl_add_u32 v88, v113, 12, v86
	s_waitcnt lgkmcnt(0)
	s_barrier
	global_load_dwordx4 v[66:69], v74, s[4:5]
	global_load_dwordx4 v[70:73], v74, s[6:7]
	ds_read_b128 v[78:81], v88
	v_and_b32_e32 v74, 64, v110
	v_add_u32_e32 v74, 64, v74
	v_xor_b32_e32 v76, 1, v110
	v_cmp_lt_i32_e32 vcc, v76, v74
	s_waitcnt lgkmcnt(0)
	v_mov_b32_e32 v77, v80
	v_mov_b32_e32 v82, v78
	v_cndmask_b32_e32 v76, v110, v76, vcc
	v_lshlrev_b32_e32 v89, 2, v76
	v_mov_b32_e32 v76, v79
	v_mov_b32_e32 v83, v81
	v_pk_add_f32 v[76:77], v[76:77], v[82:83]
	v_xor_b32_e32 v82, 2, v110
	v_add_f32_e32 v76, v76, v77
	v_cmp_lt_i32_e32 vcc, v82, v74
	v_lshl_or_b32 v87, v113, 2, 1
	s_waitcnt lgkmcnt(0)
	s_nop 1
	v_add_f32_dpp v76, v76, v76 quad_perm:[1,0,3,2] row_mask:0xf bank_mask:0xf
	v_cndmask_b32_e32 v82, v110, v82, vcc
	v_lshlrev_b32_e32 v90, 2, v82
	v_xor_b32_e32 v82, 4, v110
	v_cmp_lt_i32_e32 vcc, v82, v74
	s_waitcnt lgkmcnt(0)
	s_nop 1
	v_add_f32_dpp v76, v76, v76 quad_perm:[2,3,0,1] row_mask:0xf bank_mask:0xf
	v_cndmask_b32_e32 v82, v110, v82, vcc
	v_lshlrev_b32_e32 v91, 2, v82
	v_xor_b32_e32 v82, 8, v110
	v_cmp_lt_i32_e32 vcc, v82, v74
	s_waitcnt lgkmcnt(0)
	s_nop 1
	v_add_f32_dpp v76, v76, v76 row_half_mirror row_mask:0xf bank_mask:0xf
	v_cndmask_b32_e32 v82, v110, v82, vcc
	v_lshlrev_b32_e32 v92, 2, v82
	v_xor_b32_e32 v82, 16, v110
	v_cmp_lt_i32_e32 vcc, v82, v74
	s_waitcnt lgkmcnt(0)
	s_nop 1
	v_add_f32_dpp v76, v76, v76 row_mirror row_mask:0xf bank_mask:0xf
	v_cndmask_b32_e32 v82, v110, v82, vcc
	v_lshlrev_b32_e32 v93, 2, v82
	v_xor_b32_e32 v82, 32, v110
	v_cmp_lt_i32_e32 vcc, v82, v74
	s_nop 1
	v_cndmask_b32_e32 v74, v110, v82, vcc
	v_lshlrev_b32_e32 v94, 2, v74
	s_waitcnt lgkmcnt(0)
	v_mov_b32_e32 v77, v76
	v_mov_b32_e32 v254, v76
	s_nop 1
	v_permlane16_swap_b32 v77, v254
	v_add_f32_e32 v74, v77, v254
	s_waitcnt lgkmcnt(0)
	v_mov_b32_e32 v76, v74
	v_mov_b32_e32 v254, v74
	s_nop 1
	v_permlane32_swap_b32 v76, v254
	v_add_f32_e32 v74, v76, v254
	v_fmamk_f32 v83, v74, 0xbb800000, v79
	v_fmamk_f32 v82, v74, 0xbb800000, v78
	v_fmamk_f32 v81, v74, 0xbb800000, v81
	v_fmac_f32_e32 v80, 0xbb800000, v74
	v_pk_mul_f32 v[76:77], v[80:81], v[80:81]
	v_pk_mul_f32 v[78:79], v[82:83], v[82:83]
	s_nop 0
	v_pk_mov_b32 v[84:85], v[78:79], v[76:77] op_sel:[1,0]
	v_mov_b32_e32 v79, v77
	v_pk_add_f32 v[76:77], v[84:85], v[78:79]
	s_waitcnt vmcnt(0)
	v_mov_b32_e32 v78, v70
	v_add_f32_e32 v74, v76, v77
	v_mov_b32_e32 v77, v80
	v_mov_b32_e32 v79, v72
	v_mov_b32_e32 v80, v83
	v_mov_b32_e32 v72, v71
	s_waitcnt lgkmcnt(0)
	s_nop 1
	v_add_f32_dpp v74, v74, v74 quad_perm:[1,0,3,2] row_mask:0xf bank_mask:0xf
	s_waitcnt lgkmcnt(0)
	s_nop 1
	v_add_f32_dpp v74, v74, v74 quad_perm:[2,3,0,1] row_mask:0xf bank_mask:0xf
	s_waitcnt lgkmcnt(0)
	s_nop 1
	v_add_f32_dpp v74, v74, v74 row_half_mirror row_mask:0xf bank_mask:0xf
	s_waitcnt lgkmcnt(0)
	s_nop 1
	v_add_f32_dpp v74, v74, v74 row_mirror row_mask:0xf bank_mask:0xf
	s_waitcnt lgkmcnt(0)
	v_mov_b32_e32 v76, v74
	v_mov_b32_e32 v254, v74
	s_nop 1
	v_permlane16_swap_b32 v76, v254
	v_add_f32_e32 v74, v76, v254
	s_waitcnt lgkmcnt(0)
	v_mov_b32_e32 v76, v74
	v_mov_b32_e32 v254, v74
	s_nop 1
	v_permlane32_swap_b32 v76, v254
	v_add_f32_e32 v74, v76, v254
	v_fmamk_f32 v74, v74, 0x3b800000, v111
	v_mul_f32_e32 v76, 0x4b800000, v74
	v_cmp_gt_f32_e32 vcc, s36, v74
	s_nop 1
	v_cndmask_b32_e32 v74, v74, v76, vcc
	v_rsq_f32_e32 v74, v74
	s_nop 0
	v_mul_f32_e32 v76, 0x45800000, v74
	v_cndmask_b32_e32 v74, v74, v76, vcc
	v_mov_b32_e32 v76, v82
	v_pk_mul_f32 v[84:85], v[76:77], v[74:75] op_sel_hi:[1,0]
	v_mov_b32_e32 v76, v66
	v_mov_b32_e32 v77, v68
	v_pk_fma_f32 v[84:85], v[76:77], v[84:85], v[78:79]
	v_pk_mul_f32 v[80:81], v[80:81], v[74:75] op_sel_hi:[1,0]
	v_mul_f32_e32 v66, 0xbfb8aa3b, v84
	v_mov_b32_e32 v68, v67
	v_exp_f32_e32 v70, v66
	v_pk_fma_f32 v[66:67], v[68:69], v[80:81], v[72:73]
	v_mul_f32_e32 v74, 0xbfb8aa3b, v85
	v_mul_f32_e32 v71, 0xbfb8aa3b, v66
	v_exp_f32_e32 v71, v71
	v_exp_f32_e32 v74, v74
	v_mul_f32_e32 v80, 0xbfb8aa3b, v67
	v_exp_f32_e32 v81, v80
	v_add_f32_e32 v71, 1.0, v71
	v_add_f32_e32 v70, 1.0, v70
	v_rcp_f32_e32 v80, v71
	v_add_f32_e32 v71, 1.0, v74
	v_rcp_f32_e32 v70, v70
	v_rcp_f32_e32 v71, v71
	v_add_f32_e32 v74, 1.0, v81
	v_rcp_f32_e32 v81, v74
	v_lshl_add_u32 v74, v115, 1, s35
	v_pk_mul_f32 v[70:71], v[84:85], v[70:71]
	v_pk_mul_f32 v[66:67], v[66:67], v[80:81]
	v_and_b32_sdwa v80, v71, v112 dst_sel:DWORD dst_unused:UNUSED_PAD src0_sel:WORD_1 src1_sel:DWORD
	v_and_b32_sdwa v81, v70, v112 dst_sel:DWORD dst_unused:UNUSED_PAD src0_sel:WORD_1 src1_sel:DWORD
	v_add3_u32 v70, v70, v81, s37
	v_add3_u32 v71, v71, v80, s37
	v_and_b32_sdwa v80, v67, v112 dst_sel:DWORD dst_unused:UNUSED_PAD src0_sel:WORD_1 src1_sel:DWORD
	v_and_b32_sdwa v81, v66, v112 dst_sel:DWORD dst_unused:UNUSED_PAD src0_sel:WORD_1 src1_sel:DWORD
	v_add3_u32 v67, v67, v80, s37
	v_add3_u32 v66, v66, v81, s37
	v_and_b32_e32 v67, 0xffff0000, v67
	v_and_b32_e32 v66, 0xffff0000, v66
	v_or_b32_sdwa v67, v67, v71 dst_sel:DWORD dst_unused:UNUSED_PAD src0_sel:DWORD src1_sel:WORD_1
	v_or_b32_sdwa v66, v66, v70 dst_sel:DWORD dst_unused:UNUSED_PAD src0_sel:DWORD src1_sel:WORD_1
	v_mad_u64_u32 v[70:71], s[4:5], v113, s38, v[74:75]
	ds_write_b64 v70, v[66:67]
	v_lshl_add_u32 v66, v87, 10, v86
	ds_read_b128 v[80:83], v66
	s_waitcnt lgkmcnt(0)
	v_mov_b32_e32 v66, v81
	v_mov_b32_e32 v67, v82
	v_mov_b32_e32 v70, v80
	v_mov_b32_e32 v71, v83
	v_pk_add_f32 v[66:67], v[66:67], v[70:71]
	s_nop 0
	v_add_f32_e32 v66, v66, v67
	s_waitcnt lgkmcnt(0)
	s_nop 1
	v_add_f32_dpp v66, v66, v66 quad_perm:[1,0,3,2] row_mask:0xf bank_mask:0xf
	s_waitcnt lgkmcnt(0)
	s_nop 1
	v_add_f32_dpp v66, v66, v66 quad_perm:[2,3,0,1] row_mask:0xf bank_mask:0xf
	s_waitcnt lgkmcnt(0)
	s_nop 1
	v_add_f32_dpp v66, v66, v66 row_half_mirror row_mask:0xf bank_mask:0xf
	s_waitcnt lgkmcnt(0)
	s_nop 1
	v_add_f32_dpp v66, v66, v66 row_mirror row_mask:0xf bank_mask:0xf
	s_waitcnt lgkmcnt(0)
	v_mov_b32_e32 v67, v66
	v_mov_b32_e32 v254, v66
	s_nop 1
	v_permlane16_swap_b32 v67, v254
	v_add_f32_e32 v66, v67, v254
	s_waitcnt lgkmcnt(0)
	v_mov_b32_e32 v67, v66
	v_mov_b32_e32 v254, v66
	s_nop 1
	v_permlane32_swap_b32 v67, v254
	v_add_f32_e32 v70, v67, v254
	v_fmamk_f32 v67, v70, 0xbb800000, v81
	v_fmamk_f32 v66, v70, 0xbb800000, v80
	v_fmamk_f32 v83, v70, 0xbb800000, v83
	v_fmac_f32_e32 v82, 0xbb800000, v70
	v_pk_mul_f32 v[70:71], v[82:83], v[82:83]
	v_pk_mul_f32 v[80:81], v[66:67], v[66:67]
	s_nop 0
	v_pk_mov_b32 v[84:85], v[80:81], v[70:71] op_sel:[1,0]
	v_mov_b32_e32 v81, v71
	v_pk_add_f32 v[70:71], v[84:85], v[80:81]
	v_mov_b32_e32 v80, v66
	v_add_f32_e32 v70, v70, v71
	v_mov_b32_e32 v81, v82
	v_mov_b32_e32 v82, v67
	s_waitcnt lgkmcnt(0)
	s_nop 1
	v_add_f32_dpp v70, v70, v70 quad_perm:[1,0,3,2] row_mask:0xf bank_mask:0xf
	s_waitcnt lgkmcnt(0)
	s_nop 1
	v_add_f32_dpp v70, v70, v70 quad_perm:[2,3,0,1] row_mask:0xf bank_mask:0xf
	s_waitcnt lgkmcnt(0)
	s_nop 1
	v_add_f32_dpp v70, v70, v70 row_half_mirror row_mask:0xf bank_mask:0xf
	s_waitcnt lgkmcnt(0)
	s_nop 1
	v_add_f32_dpp v70, v70, v70 row_mirror row_mask:0xf bank_mask:0xf
	s_waitcnt lgkmcnt(0)
	v_mov_b32_e32 v71, v70
	v_mov_b32_e32 v254, v70
	s_nop 1
	v_permlane16_swap_b32 v71, v254
	v_add_f32_e32 v70, v71, v254
	s_waitcnt lgkmcnt(0)
	v_mov_b32_e32 v71, v70
	v_mov_b32_e32 v254, v70
	s_nop 1
	v_permlane32_swap_b32 v71, v254
	v_add_f32_e32 v70, v71, v254
	v_fmamk_f32 v70, v70, 0x3b800000, v111
	v_mul_f32_e32 v71, 0x4b800000, v70
	v_cmp_gt_f32_e32 vcc, s36, v70
	s_nop 1
	v_cndmask_b32_e32 v70, v70, v71, vcc
	v_rsq_f32_e32 v70, v70
	s_nop 0
	v_mul_f32_e32 v71, 0x45800000, v70
	v_cndmask_b32_e32 v70, v70, v71, vcc
	v_pk_mul_f32 v[80:81], v[80:81], v[70:71] op_sel_hi:[1,0]
	s_nop 0
	v_pk_fma_f32 v[80:81], v[76:77], v[80:81], v[78:79]
	s_nop 0
	v_mul_f32_e32 v66, 0xbfb8aa3b, v80
	v_exp_f32_e32 v71, v66
	s_nop 0
	v_pk_mul_f32 v[66:67], v[82:83], v[70:71] op_sel_hi:[1,0]
	s_nop 0
	v_pk_fma_f32 v[66:67], v[68:69], v[66:67], v[72:73]
	s_nop 0
	v_mul_f32_e32 v70, 0xbfb8aa3b, v66
	v_exp_f32_e32 v82, v70
	v_add_f32_e32 v70, 1.0, v71
	v_rcp_f32_e32 v70, v70
	v_add_f32_e32 v71, 1.0, v82
	v_mul_f32_e32 v82, 0xbfb8aa3b, v81
	v_exp_f32_e32 v83, v82
	v_mul_f32_e32 v82, 0xbfb8aa3b, v67
	v_exp_f32_e32 v84, v82
	v_rcp_f32_e32 v82, v71
	v_add_f32_e32 v71, 1.0, v83
	v_rcp_f32_e32 v71, v71
	v_add_f32_e32 v83, 1.0, v84
	v_rcp_f32_e32 v83, v83
	v_pk_mul_f32 v[70:71], v[80:81], v[70:71]
	s_nop 0
	v_and_b32_sdwa v80, v71, v112 dst_sel:DWORD dst_unused:UNUSED_PAD src0_sel:WORD_1 src1_sel:DWORD
	v_pk_mul_f32 v[66:67], v[66:67], v[82:83]
	v_and_b32_sdwa v81, v70, v112 dst_sel:DWORD dst_unused:UNUSED_PAD src0_sel:WORD_1 src1_sel:DWORD
	v_add3_u32 v70, v70, v81, s37
	v_add3_u32 v71, v71, v80, s37
	v_and_b32_sdwa v80, v67, v112 dst_sel:DWORD dst_unused:UNUSED_PAD src0_sel:WORD_1 src1_sel:DWORD
	v_and_b32_sdwa v81, v66, v112 dst_sel:DWORD dst_unused:UNUSED_PAD src0_sel:WORD_1 src1_sel:DWORD
	v_add3_u32 v67, v67, v80, s37
	v_add3_u32 v66, v66, v81, s37
	v_and_b32_e32 v67, 0xffff0000, v67
	v_and_b32_e32 v66, 0xffff0000, v66
	v_or_b32_sdwa v67, v67, v71 dst_sel:DWORD dst_unused:UNUSED_PAD src0_sel:DWORD src1_sel:WORD_1
	v_or_b32_sdwa v66, v66, v70 dst_sel:DWORD dst_unused:UNUSED_PAD src0_sel:DWORD src1_sel:WORD_1
	v_mad_u64_u32 v[70:71], s[4:5], v87, s39, v[74:75]
	ds_write_b64 v70, v[66:67]
	ds_read_b128 v[80:83], v88 offset:2048
	s_waitcnt lgkmcnt(0)
	v_mov_b32_e32 v66, v81
	v_mov_b32_e32 v67, v82
	v_mov_b32_e32 v84, v80
	v_mov_b32_e32 v85, v83
	v_pk_add_f32 v[66:67], v[66:67], v[84:85]
	s_nop 0
	v_add_f32_e32 v66, v66, v67
	s_waitcnt lgkmcnt(0)
	s_nop 1
	v_add_f32_dpp v66, v66, v66 quad_perm:[1,0,3,2] row_mask:0xf bank_mask:0xf
	s_waitcnt lgkmcnt(0)
	s_nop 1
	v_add_f32_dpp v66, v66, v66 quad_perm:[2,3,0,1] row_mask:0xf bank_mask:0xf
	s_waitcnt lgkmcnt(0)
	s_nop 1
	v_add_f32_dpp v66, v66, v66 row_half_mirror row_mask:0xf bank_mask:0xf
	s_waitcnt lgkmcnt(0)
	s_nop 1
	v_add_f32_dpp v66, v66, v66 row_mirror row_mask:0xf bank_mask:0xf
	s_waitcnt lgkmcnt(0)
	v_mov_b32_e32 v67, v66
	v_mov_b32_e32 v254, v66
	s_nop 1
	v_permlane16_swap_b32 v67, v254
	v_add_f32_e32 v66, v67, v254
	s_waitcnt lgkmcnt(0)
	v_mov_b32_e32 v67, v66
	v_mov_b32_e32 v254, v66
	s_nop 1
	v_permlane32_swap_b32 v67, v254
	v_add_f32_e32 v71, v67, v254
	v_fmamk_f32 v67, v71, 0xbb800000, v81
	v_fmamk_f32 v66, v71, 0xbb800000, v80
	v_fmamk_f32 v83, v71, 0xbb800000, v83
	v_fmac_f32_e32 v82, 0xbb800000, v71
	v_pk_mul_f32 v[80:81], v[82:83], v[82:83]
	v_pk_mul_f32 v[84:85], v[66:67], v[66:67]
	s_nop 0
	v_pk_mov_b32 v[86:87], v[84:85], v[80:81] op_sel:[1,0]
	v_mov_b32_e32 v85, v81
	v_pk_add_f32 v[80:81], v[86:87], v[84:85]
	s_nop 0
	v_add_f32_e32 v71, v80, v81
	v_mov_b32_e32 v80, v66
	v_mov_b32_e32 v81, v82
	v_mov_b32_e32 v82, v67
	s_waitcnt lgkmcnt(0)
	s_nop 1
	v_add_f32_dpp v71, v71, v71 quad_perm:[1,0,3,2] row_mask:0xf bank_mask:0xf
	s_waitcnt lgkmcnt(0)
	s_nop 1
	v_add_f32_dpp v71, v71, v71 quad_perm:[2,3,0,1] row_mask:0xf bank_mask:0xf
	s_waitcnt lgkmcnt(0)
	s_nop 1
	v_add_f32_dpp v71, v71, v71 row_half_mirror row_mask:0xf bank_mask:0xf
	s_waitcnt lgkmcnt(0)
	s_nop 1
	v_add_f32_dpp v71, v71, v71 row_mirror row_mask:0xf bank_mask:0xf
	s_waitcnt lgkmcnt(0)
	v_mov_b32_e32 v74, v71
	v_mov_b32_e32 v254, v71
	s_nop 1
	v_permlane16_swap_b32 v74, v254
	v_add_f32_e32 v71, v74, v254
	s_waitcnt lgkmcnt(0)
	v_mov_b32_e32 v74, v71
	v_mov_b32_e32 v254, v71
	s_nop 1
	v_permlane32_swap_b32 v74, v254
	v_add_f32_e32 v71, v74, v254
	v_fmamk_f32 v71, v71, 0x3b800000, v111
	v_mul_f32_e32 v74, 0x4b800000, v71
	v_cmp_gt_f32_e32 vcc, s36, v71
	s_nop 1
	v_cndmask_b32_e32 v71, v71, v74, vcc
	v_rsq_f32_e32 v71, v71
	s_nop 0
	v_mul_f32_e32 v74, 0x45800000, v71
	v_cndmask_b32_e32 v74, v71, v74, vcc
	v_pk_mul_f32 v[80:81], v[80:81], v[74:75] op_sel_hi:[1,0]
	s_nop 0
	v_pk_fma_f32 v[80:81], v[76:77], v[80:81], v[78:79]
	s_nop 0
	v_mul_f32_e32 v66, 0xbfb8aa3b, v80
	v_exp_f32_e32 v71, v66
	v_pk_mul_f32 v[66:67], v[82:83], v[74:75] op_sel_hi:[1,0]
	v_add_f32_e32 v71, 1.0, v71
	v_pk_fma_f32 v[66:67], v[68:69], v[66:67], v[72:73]
	v_rcp_f32_e32 v82, v71
	v_mul_f32_e32 v74, 0xbfb8aa3b, v66
	v_exp_f32_e32 v74, v74
	v_mul_f32_e32 v83, 0xbfb8aa3b, v67
	v_exp_f32_e32 v85, v83
	v_add_f32_e32 v71, 1.0, v74
	v_mul_f32_e32 v74, 0xbfb8aa3b, v81
	v_exp_f32_e32 v74, v74
	v_rcp_f32_e32 v84, v71
	v_add_f32_e32 v71, 1.0, v74
	v_rcp_f32_e32 v83, v71
	v_add_f32_e32 v71, 1.0, v85
	v_rcp_f32_e32 v85, v71
	v_pk_mul_f32 v[80:81], v[80:81], v[82:83]
	s_nop 0
	v_and_b32_sdwa v71, v81, v112 dst_sel:DWORD dst_unused:UNUSED_PAD src0_sel:WORD_1 src1_sel:DWORD
	v_pk_mul_f32 v[66:67], v[66:67], v[84:85]
	v_and_b32_sdwa v74, v80, v112 dst_sel:DWORD dst_unused:UNUSED_PAD src0_sel:WORD_1 src1_sel:DWORD
	v_add3_u32 v74, v80, v74, s37
	v_add3_u32 v71, v81, v71, s37
	v_and_b32_sdwa v80, v67, v112 dst_sel:DWORD dst_unused:UNUSED_PAD src0_sel:WORD_1 src1_sel:DWORD
	v_and_b32_sdwa v81, v66, v112 dst_sel:DWORD dst_unused:UNUSED_PAD src0_sel:WORD_1 src1_sel:DWORD
	v_add3_u32 v67, v67, v80, s37
	v_add3_u32 v66, v66, v81, s37
	v_and_b32_e32 v67, 0xffff0000, v67
	v_and_b32_e32 v66, 0xffff0000, v66
	v_or_b32_sdwa v67, v67, v71 dst_sel:DWORD dst_unused:UNUSED_PAD src0_sel:DWORD src1_sel:WORD_1
	v_or_b32_sdwa v66, v66, v74 dst_sel:DWORD dst_unused:UNUSED_PAD src0_sel:DWORD src1_sel:WORD_1
	ds_write_b64 v70, v[66:67] offset:528
	ds_read_b128 v[80:83], v88 offset:3072
	s_waitcnt lgkmcnt(0)
	v_mov_b32_e32 v66, v81
	v_mov_b32_e32 v67, v82
	v_mov_b32_e32 v84, v80
	v_mov_b32_e32 v85, v83
	v_pk_add_f32 v[66:67], v[66:67], v[84:85]
	s_nop 0
	v_add_f32_e32 v66, v66, v67
	s_waitcnt lgkmcnt(0)
	s_nop 1
	v_add_f32_dpp v66, v66, v66 quad_perm:[1,0,3,2] row_mask:0xf bank_mask:0xf
	s_waitcnt lgkmcnt(0)
	s_nop 1
	v_add_f32_dpp v66, v66, v66 quad_perm:[2,3,0,1] row_mask:0xf bank_mask:0xf
	s_waitcnt lgkmcnt(0)
	s_nop 1
	v_add_f32_dpp v66, v66, v66 row_half_mirror row_mask:0xf bank_mask:0xf
	s_waitcnt lgkmcnt(0)
	s_nop 1
	v_add_f32_dpp v66, v66, v66 row_mirror row_mask:0xf bank_mask:0xf
	s_waitcnt lgkmcnt(0)
	v_mov_b32_e32 v67, v66
	v_mov_b32_e32 v254, v66
	s_nop 1
	v_permlane16_swap_b32 v67, v254
	v_add_f32_e32 v66, v67, v254
	s_waitcnt lgkmcnt(0)
	v_mov_b32_e32 v67, v66
	v_mov_b32_e32 v254, v66
	s_nop 1
	v_permlane32_swap_b32 v67, v254
	v_add_f32_e32 v71, v67, v254
	v_fmamk_f32 v67, v71, 0xbb800000, v81
	v_fmamk_f32 v66, v71, 0xbb800000, v80
	v_fmamk_f32 v83, v71, 0xbb800000, v83
	v_fmac_f32_e32 v82, 0xbb800000, v71
	v_pk_mul_f32 v[80:81], v[82:83], v[82:83]
	v_pk_mul_f32 v[84:85], v[66:67], v[66:67]
	s_nop 0
	v_pk_mov_b32 v[86:87], v[84:85], v[80:81] op_sel:[1,0]
	v_mov_b32_e32 v85, v81
	v_pk_add_f32 v[80:81], v[86:87], v[84:85]
	s_nop 0
	v_add_f32_e32 v71, v80, v81
	v_mov_b32_e32 v80, v66
	v_mov_b32_e32 v81, v82
	v_mov_b32_e32 v82, v67
	s_waitcnt lgkmcnt(0)
	s_nop 1
	v_add_f32_dpp v71, v71, v71 quad_perm:[1,0,3,2] row_mask:0xf bank_mask:0xf
	s_waitcnt lgkmcnt(0)
	s_nop 1
	v_add_f32_dpp v71, v71, v71 quad_perm:[2,3,0,1] row_mask:0xf bank_mask:0xf
	s_waitcnt lgkmcnt(0)
	s_nop 1
	v_add_f32_dpp v71, v71, v71 row_half_mirror row_mask:0xf bank_mask:0xf
	s_waitcnt lgkmcnt(0)
	s_nop 1
	v_add_f32_dpp v71, v71, v71 row_mirror row_mask:0xf bank_mask:0xf
	s_waitcnt lgkmcnt(0)
	v_mov_b32_e32 v74, v71
	v_mov_b32_e32 v254, v71
	s_nop 1
	v_permlane16_swap_b32 v74, v254
	v_add_f32_e32 v71, v74, v254
	s_waitcnt lgkmcnt(0)
	v_mov_b32_e32 v74, v71
	v_mov_b32_e32 v254, v71
	s_nop 1
	v_permlane32_swap_b32 v74, v254
	v_add_f32_e32 v71, v74, v254
	v_fmamk_f32 v71, v71, 0x3b800000, v111
	v_mul_f32_e32 v74, 0x4b800000, v71
	v_cmp_gt_f32_e32 vcc, s36, v71
	s_nop 1
	v_cndmask_b32_e32 v71, v71, v74, vcc
	v_rsq_f32_e32 v71, v71
	s_nop 0
	v_mul_f32_e32 v74, 0x45800000, v71
	v_cndmask_b32_e32 v74, v71, v74, vcc
	v_pk_mul_f32 v[80:81], v[80:81], v[74:75] op_sel_hi:[1,0]
	s_nop 0
	v_pk_fma_f32 v[76:77], v[76:77], v[80:81], v[78:79]
	s_nop 0
	v_mul_f32_e32 v66, 0xbfb8aa3b, v76
	v_exp_f32_e32 v71, v66
	v_pk_mul_f32 v[66:67], v[82:83], v[74:75] op_sel_hi:[1,0]
	v_and_b32_e32 v74, 15, v114
	v_pk_fma_f32 v[66:67], v[68:69], v[66:67], v[72:73]
	s_nop 0
	v_mul_f32_e32 v68, 0xbfb8aa3b, v66
	v_exp_f32_e32 v69, v68
	v_add_f32_e32 v68, 1.0, v71
	v_mul_f32_e32 v71, 0xbfb8aa3b, v77
	v_exp_f32_e32 v71, v71
	v_mul_f32_e32 v72, 0xbfb8aa3b, v67
	v_exp_f32_e32 v73, v72
	v_add_f32_e32 v69, 1.0, v69
	v_rcp_f32_e32 v72, v69
	v_add_f32_e32 v69, 1.0, v71
	v_rcp_f32_e32 v68, v68
	v_rcp_f32_e32 v69, v69
	v_add_f32_e32 v71, 1.0, v73
	v_rcp_f32_e32 v73, v71
	v_pk_mul_f32 v[68:69], v[76:77], v[68:69]
	s_nop 0
	v_and_b32_sdwa v71, v69, v112 dst_sel:DWORD dst_unused:UNUSED_PAD src0_sel:WORD_1 src1_sel:DWORD
	v_pk_mul_f32 v[66:67], v[66:67], v[72:73]
	v_and_b32_sdwa v72, v68, v112 dst_sel:DWORD dst_unused:UNUSED_PAD src0_sel:WORD_1 src1_sel:DWORD
	v_add3_u32 v68, v68, v72, s37
	v_add3_u32 v69, v69, v71, s37
	v_and_b32_sdwa v71, v67, v112 dst_sel:DWORD dst_unused:UNUSED_PAD src0_sel:WORD_1 src1_sel:DWORD
	v_and_b32_sdwa v72, v66, v112 dst_sel:DWORD dst_unused:UNUSED_PAD src0_sel:WORD_1 src1_sel:DWORD
	v_add3_u32 v67, v67, v71, s37
	v_add3_u32 v66, v66, v72, s37
	v_and_b32_e32 v67, 0xffff0000, v67
	v_and_b32_e32 v66, 0xffff0000, v66
	v_or_b32_sdwa v67, v67, v69 dst_sel:DWORD dst_unused:UNUSED_PAD src0_sel:DWORD src1_sel:WORD_1
	v_or_b32_sdwa v66, v66, v68 dst_sel:DWORD dst_unused:UNUSED_PAD src0_sel:DWORD src1_sel:WORD_1
	ds_write_b64 v70, v[66:67] offset:1056
	v_and_b32_e32 v66, 48, v114
	v_mul_u32_u24_e32 v67, 0x210, v74
	v_add3_u32 v100, s35, v66, v67
	s_waitcnt lgkmcnt(0)
	s_barrier
	ds_read_b128 v[66:69], v100
	ds_read_b128 v[70:73], v100 offset:64
	ds_read_b128 v[80:83], v100 offset:8448
	ds_read_b128 v[84:87], v100 offset:8512
	s_waitcnt lgkmcnt(3)
	v_mfma_f32_16x16x32_bf16 v[76:79], v[2:5], v[66:69], 0
	s_waitcnt lgkmcnt(1)
	v_mfma_f32_16x16x32_bf16 v[88:91], v[2:5], v[80:83], 0
	v_mfma_f32_16x16x32_bf16 v[66:69], v[34:37], v[66:69], 0
	v_mfma_f32_16x16x32_bf16 v[80:83], v[34:37], v[80:83], 0
	v_mfma_f32_16x16x32_bf16 v[76:79], v[6:9], v[70:73], v[76:79]
	s_waitcnt lgkmcnt(0)
	v_mfma_f32_16x16x32_bf16 v[88:91], v[6:9], v[84:87], v[88:91]
	v_mfma_f32_16x16x32_bf16 v[66:69], v[38:41], v[70:73], v[66:69]
	v_mfma_f32_16x16x32_bf16 v[70:73], v[38:41], v[84:87], v[80:83]
	s_nop 2
	ds_read_b128 v[80:83], v100 offset:128
	ds_read_b128 v[84:87], v100 offset:192
	ds_read_b128 v[92:95], v100 offset:8576
	ds_read_b128 v[96:99], v100 offset:8640
	s_waitcnt lgkmcnt(3)
	v_mfma_f32_16x16x32_bf16 v[76:79], v[10:13], v[80:83], v[76:79]
	s_waitcnt lgkmcnt(1)
	v_mfma_f32_16x16x32_bf16 v[88:91], v[10:13], v[92:95], v[88:91]
	v_mfma_f32_16x16x32_bf16 v[66:69], v[42:45], v[80:83], v[66:69]
	v_mfma_f32_16x16x32_bf16 v[70:73], v[42:45], v[92:95], v[70:73]
	v_mfma_f32_16x16x32_bf16 v[76:79], v[14:17], v[84:87], v[76:79]
	s_waitcnt lgkmcnt(0)
	v_mfma_f32_16x16x32_bf16 v[80:83], v[14:17], v[96:99], v[88:91]
	v_mfma_f32_16x16x32_bf16 v[66:69], v[46:49], v[84:87], v[66:69]
	ds_read_b128 v[84:87], v100 offset:256
	s_nop 0
	ds_read_b128 v[88:91], v100 offset:320
	v_mfma_f32_16x16x32_bf16 v[70:73], v[46:49], v[96:99], v[70:73]
	ds_read_b128 v[92:95], v100 offset:8704
	ds_read_b128 v[96:99], v100 offset:8768
	s_waitcnt lgkmcnt(3)
	v_mfma_f32_16x16x32_bf16 v[76:79], v[18:21], v[84:87], v[76:79]
	v_mfma_f32_16x16x32_bf16 v[66:69], v[50:53], v[84:87], v[66:69]
	s_waitcnt lgkmcnt(1)
	v_mfma_f32_16x16x32_bf16 v[80:83], v[18:21], v[92:95], v[80:83]
	v_mfma_f32_16x16x32_bf16 v[70:73], v[50:53], v[92:95], v[70:73]
	v_mfma_f32_16x16x32_bf16 v[76:79], v[22:25], v[88:91], v[76:79]
	v_mfma_f32_16x16x32_bf16 v[66:69], v[54:57], v[88:91], v[66:69]
	ds_read_b128 v[84:87], v100 offset:384
	ds_read_b128 v[88:91], v100 offset:448
	s_waitcnt lgkmcnt(2)
	v_mfma_f32_16x16x32_bf16 v[80:83], v[22:25], v[96:99], v[80:83]
	v_mfma_f32_16x16x32_bf16 v[70:73], v[54:57], v[96:99], v[70:73]
	ds_read_b128 v[92:95], v100 offset:8832
	ds_read_b128 v[96:99], v100 offset:8896
	s_waitcnt lgkmcnt(3)
	v_mfma_f32_16x16x32_bf16 v[76:79], v[26:29], v[84:87], v[76:79]
	v_mfma_f32_16x16x32_bf16 v[66:69], v[58:61], v[84:87], v[66:69]
	v_lshrrev_b32_e32 v84, 2, v114
	v_and_b32_e32 v84, 12, v84
	s_waitcnt lgkmcnt(1)
	v_mfma_f32_16x16x32_bf16 v[80:83], v[26:29], v[92:95], v[80:83]
	v_mfma_f32_16x16x32_bf16 v[70:73], v[58:61], v[92:95], v[70:73]
	v_lshl_or_b32 v92, v113, 5, v84
	v_ashrrev_i32_e32 v93, 31, v92
	v_lshl_add_u64 v[94:95], v[92:93], 2, s[10:11]
	global_load_dwordx4 v[84:87], v[94:95], off
	v_mfma_f32_16x16x32_bf16 v[76:79], v[30:33], v[88:91], v[76:79]
	v_mfma_f32_16x16x32_bf16 v[66:69], v[62:65], v[88:91], v[66:69]
	v_or_b32_e32 v88, s41, v74
	s_waitcnt vmcnt(0)
	s_nop 4
	v_pk_add_f32 v[78:79], v[78:79], v[86:87]
	v_pk_add_f32 v[76:77], v[76:77], v[84:85]
	v_and_b32_sdwa v74, v78, v112 dst_sel:DWORD dst_unused:UNUSED_PAD src0_sel:WORD_1 src1_sel:DWORD
	v_and_b32_sdwa v89, v76, v112 dst_sel:DWORD dst_unused:UNUSED_PAD src0_sel:WORD_1 src1_sel:DWORD
	v_add3_u32 v76, v76, v89, s37
	v_add3_u32 v74, v78, v74, s37
	v_and_b32_sdwa v78, v79, v112 dst_sel:DWORD dst_unused:UNUSED_PAD src0_sel:WORD_1 src1_sel:DWORD
	v_and_b32_sdwa v89, v77, v112 dst_sel:DWORD dst_unused:UNUSED_PAD src0_sel:WORD_1 src1_sel:DWORD
	v_add3_u32 v78, v79, v78, s37
	v_add3_u32 v77, v77, v89, s37
	s_waitcnt lgkmcnt(0)
	v_mfma_f32_16x16x32_bf16 v[80:83], v[30:33], v[96:99], v[80:83]
	v_and_b32_e32 v78, 0xffff0000, v78
	v_and_b32_e32 v79, 0xffff0000, v77
	v_ashrrev_i32_e32 v89, 31, v88
	v_or_b32_sdwa v77, v78, v74 dst_sel:DWORD dst_unused:UNUSED_PAD src0_sel:DWORD src1_sel:WORD_1
	v_or_b32_sdwa v76, v79, v76 dst_sel:DWORD dst_unused:UNUSED_PAD src0_sel:DWORD src1_sel:WORD_1
	v_lshlrev_b64 v[78:79], 11, v[88:89]
	v_lshl_add_u64 v[78:79], s[88:89], 0, v[78:79]
	v_lshl_add_u64 v[90:91], v[78:79], 0, s[0:1]
	v_lshlrev_b64 v[78:79], 1, v[92:93]
	v_lshl_add_u64 v[100:101], v[90:91], 0, v[78:79]
	v_pk_add_f32 v[82:83], v[82:83], v[86:87]
	v_pk_add_f32 v[80:81], v[80:81], v[84:85]
	global_store_dwordx2 v[100:101], v[76:77], off
	v_and_b32_sdwa v74, v82, v112 dst_sel:DWORD dst_unused:UNUSED_PAD src0_sel:WORD_1 src1_sel:DWORD
	v_and_b32_sdwa v77, v80, v112 dst_sel:DWORD dst_unused:UNUSED_PAD src0_sel:WORD_1 src1_sel:DWORD
	v_add3_u32 v77, v80, v77, s37
	v_add3_u32 v74, v82, v74, s37
	v_and_b32_sdwa v80, v83, v112 dst_sel:DWORD dst_unused:UNUSED_PAD src0_sel:WORD_1 src1_sel:DWORD
	v_and_b32_sdwa v82, v81, v112 dst_sel:DWORD dst_unused:UNUSED_PAD src0_sel:WORD_1 src1_sel:DWORD
	v_add3_u32 v80, v83, v80, s37
	v_add3_u32 v81, v81, v82, s37
	v_or_b32_e32 v76, 16, v88
	v_and_b32_e32 v80, 0xffff0000, v80
	v_and_b32_e32 v82, 0xffff0000, v81
	v_or_b32_sdwa v81, v80, v74 dst_sel:DWORD dst_unused:UNUSED_PAD src0_sel:DWORD src1_sel:WORD_1
	v_or_b32_sdwa v80, v82, v77 dst_sel:DWORD dst_unused:UNUSED_PAD src0_sel:DWORD src1_sel:WORD_1
	v_ashrrev_i32_e32 v77, 31, v76
	v_lshlrev_b64 v[76:77], 11, v[76:77]
	v_lshl_add_u64 v[76:77], s[88:89], 0, v[76:77]
	v_lshl_add_u64 v[82:83], v[76:77], 0, s[0:1]
	v_lshl_add_u64 v[76:77], v[82:83], 0, v[78:79]
	global_store_dwordx2 v[76:77], v[80:81], off
	global_load_dwordx4 v[76:79], v[94:95], off offset:64
	v_mfma_f32_16x16x32_bf16 v[70:73], v[62:65], v[96:99], v[70:73]
	v_or_b32_e32 v80, 16, v92
	v_ashrrev_i32_e32 v81, 31, v80
	s_waitcnt vmcnt(0)
	v_pk_add_f32 v[68:69], v[68:69], v[78:79]
	v_pk_add_f32 v[66:67], v[66:67], v[76:77]
	v_and_b32_sdwa v74, v68, v112 dst_sel:DWORD dst_unused:UNUSED_PAD src0_sel:WORD_1 src1_sel:DWORD
	v_and_b32_sdwa v84, v66, v112 dst_sel:DWORD dst_unused:UNUSED_PAD src0_sel:WORD_1 src1_sel:DWORD
	v_add3_u32 v68, v68, v74, s37
	v_and_b32_sdwa v74, v69, v112 dst_sel:DWORD dst_unused:UNUSED_PAD src0_sel:WORD_1 src1_sel:DWORD
	v_add3_u32 v66, v66, v84, s37
	v_and_b32_sdwa v84, v67, v112 dst_sel:DWORD dst_unused:UNUSED_PAD src0_sel:WORD_1 src1_sel:DWORD
	v_add3_u32 v69, v69, v74, s37
	v_add3_u32 v67, v67, v84, s37
	v_and_b32_e32 v69, 0xffff0000, v69
	v_and_b32_e32 v74, 0xffff0000, v67
	v_or_b32_sdwa v67, v69, v68 dst_sel:DWORD dst_unused:UNUSED_PAD src0_sel:DWORD src1_sel:WORD_1
	v_lshlrev_b64 v[68:69], 1, v[80:81]
	v_or_b32_sdwa v66, v74, v66 dst_sel:DWORD dst_unused:UNUSED_PAD src0_sel:DWORD src1_sel:WORD_1
	v_lshl_add_u64 v[80:81], v[90:91], 0, v[68:69]
	global_store_dwordx2 v[80:81], v[66:67], off
	v_pk_add_f32 v[66:67], v[72:73], v[78:79]
	v_pk_add_f32 v[70:71], v[70:71], v[76:77]
	v_and_b32_sdwa v72, v66, v112 dst_sel:DWORD dst_unused:UNUSED_PAD src0_sel:WORD_1 src1_sel:DWORD
	v_and_b32_sdwa v73, v70, v112 dst_sel:DWORD dst_unused:UNUSED_PAD src0_sel:WORD_1 src1_sel:DWORD
	v_add3_u32 v70, v70, v73, s37
	v_add3_u32 v66, v66, v72, s37
	v_and_b32_sdwa v72, v67, v112 dst_sel:DWORD dst_unused:UNUSED_PAD src0_sel:WORD_1 src1_sel:DWORD
	v_and_b32_sdwa v73, v71, v112 dst_sel:DWORD dst_unused:UNUSED_PAD src0_sel:WORD_1 src1_sel:DWORD
	v_add3_u32 v67, v67, v72, s37
	v_add3_u32 v71, v71, v73, s37
	v_and_b32_e32 v67, 0xffff0000, v67
	v_and_b32_e32 v71, 0xffff0000, v71
	v_or_b32_sdwa v67, v67, v66 dst_sel:DWORD dst_unused:UNUSED_PAD src0_sel:DWORD src1_sel:WORD_1
	v_or_b32_sdwa v66, v71, v70 dst_sel:DWORD dst_unused:UNUSED_PAD src0_sel:DWORD src1_sel:WORD_1
	v_lshl_add_u64 v[68:69], v[82:83], 0, v[68:69]
	global_store_dwordx2 v[68:69], v[66:67], off
	s_barrier
	s_cbranch_scc0 .LBB0_755

.LBB0_1964:
	s_or_b64 exec, exec, s[4:5]
	v_and_b32_e32 v74, 0x3fc, v100
	s_waitcnt vmcnt(0)
	v_lshl_add_u64 v[66:67], s[0:1], 0, v[74:75]
	v_add_co_u32_e32 v68, vcc, 0x1000, v66
	s_waitcnt lgkmcnt(0)
	s_nop 0
	v_addc_co_u32_e32 v69, vcc, 0, v67, vcc
	v_add_co_u32_e32 v70, vcc, 0x2000, v66
	s_barrier
	s_nop 0
	v_addc_co_u32_e32 v71, vcc, 0, v67, vcc
	global_load_dword v123, v[68:69], off
	global_load_dword v122, v[68:69], off offset:1024
	global_load_dword v120, v[68:69], off offset:2048
	global_load_dword v118, v[68:69], off offset:3072
	global_load_dword v121, v[70:71], off
	global_load_dword v119, v[70:71], off offset:1024
	global_load_dword v117, v[70:71], off offset:2048
	global_load_dword v116, v[70:71], off offset:3072
	global_load_dword v128, v74, s[0:1]
	global_load_dword v127, v74, s[0:1] offset:1024
	global_load_dword v126, v74, s[0:1] offset:2048
	global_load_dword v125, v74, s[0:1] offset:3072
	v_add_co_u32_e32 v68, vcc, 0x3000, v66
	v_readlane_b32 s4, v239, 1
	s_nop 0
	v_addc_co_u32_e32 v69, vcc, 0, v67, vcc
	v_add_co_u32_e32 v70, vcc, s30, v66
	v_readlane_b32 s18, v239, 15
	v_readlane_b32 s19, v239, 16
	v_addc_co_u32_e32 v71, vcc, 0, v67, vcc
	s_nop 3
	global_load_dword v124, v74, s[18:19] offset:1024
	global_load_dword v147, v[68:69], off
	global_load_dword v146, v[68:69], off offset:1024
	global_load_dword v144, v[68:69], off offset:2048
	global_load_dword v142, v[68:69], off offset:3072
	global_load_dword v140, v[70:71], off
	global_load_dword v138, v[70:71], off offset:1024
	global_load_dword v136, v[70:71], off offset:2048
	global_load_dword v133, v[70:71], off offset:3072
	v_add_co_u32_e32 v68, vcc, 0x5000, v66
	v_readlane_b32 s5, v239, 2
	s_nop 0
	v_addc_co_u32_e32 v69, vcc, 0, v67, vcc
	v_add_co_u32_e32 v70, vcc, 0x6000, v66
	v_readlane_b32 s6, v239, 3
	s_nop 0
	v_addc_co_u32_e32 v71, vcc, 0, v67, vcc
	global_load_dword v145, v[68:69], off
	global_load_dword v143, v[68:69], off offset:1024
	global_load_dword v141, v[68:69], off offset:2048
	global_load_dword v139, v[68:69], off offset:3072
	global_load_dword v137, v[70:71], off
	global_load_dword v134, v[70:71], off offset:1024
	global_load_dword v131, v[70:71], off offset:2048
	global_load_dword v129, v[70:71], off offset:3072
	v_add_co_u32_e32 v66, vcc, 0x7000, v66
	v_readlane_b32 s7, v239, 4
	s_nop 0
	v_addc_co_u32_e32 v67, vcc, 0, v67, vcc
	global_load_dword v135, v[66:67], off
	global_load_dword v132, v[66:67], off offset:1024
	global_load_dword v130, v[66:67], off offset:2048
	v_lshlrev_b32_e32 v66, 6, v114
	v_and_b32_e32 v152, 0xffffc000, v66
	v_add3_u32 v66, 0, v152, v74
	ds_read2st64_b32 v[148:149], v66 offset1:4
	ds_read2st64_b32 v[150:151], v66 offset0:8 offset1:12
	ds_read2st64_b32 v[108:109], v66 offset0:16 offset1:20
	ds_read2st64_b32 v[106:107], v66 offset0:24 offset1:28
	ds_read2st64_b32 v[104:105], v66 offset0:32 offset1:36
	ds_read2st64_b32 v[102:103], v66 offset0:40 offset1:44
	ds_read2st64_b32 v[100:101], v66 offset0:48 offset1:52
	ds_read2st64_b32 v[98:99], v66 offset0:56 offset1:60
	ds_read2st64_b32 v[96:97], v66 offset0:64 offset1:68
	ds_read2st64_b32 v[94:95], v66 offset0:72 offset1:76
	ds_read2st64_b32 v[92:93], v66 offset0:80 offset1:84
	ds_read2st64_b32 v[90:91], v66 offset0:88 offset1:92
	ds_read2st64_b32 v[88:89], v66 offset0:96 offset1:100
	ds_read2st64_b32 v[86:87], v66 offset0:104 offset1:108
	ds_read2st64_b32 v[84:85], v66 offset0:112 offset1:116
	ds_read2st64_b32 v[82:83], v66 offset0:120 offset1:124
	ds_read2st64_b32 v[80:81], v66 offset0:128 offset1:132
	ds_read2st64_b32 v[78:79], v66 offset0:136 offset1:140
	ds_read2st64_b32 v[76:77], v66 offset0:144 offset1:148
	ds_read2st64_b32 v[72:73], v66 offset0:152 offset1:156
	ds_read2st64_b32 v[70:71], v66 offset0:160 offset1:164
	ds_read2st64_b32 v[68:69], v66 offset0:168 offset1:172
	ds_read2st64_b32 v[66:67], v66 offset0:176 offset1:180
	v_add3_u32 v74, s40, v152, v74
	v_readlane_b32 s8, v239, 5
	v_readlane_b32 s9, v239, 6
	v_readlane_b32 s10, v239, 7
	v_readlane_b32 s11, v239, 8
	v_readlane_b32 s12, v239, 9
	v_readlane_b32 s13, v239, 10
	v_readlane_b32 s14, v239, 11
	v_readlane_b32 s15, v239, 12
	v_readlane_b32 s16, v239, 13
	v_readlane_b32 s17, v239, 14
	v_readlane_b32 s4, v239, 49
	v_readlane_b32 s5, v239, 50
	v_readlane_b32 s6, v239, 51
	v_readlane_b32 s7, v239, 52
	v_readlane_b32 s10, v239, 55
	v_readlane_b32 s11, v239, 56
	s_add_i32 s46, s46, s68
	v_readlane_b32 s8, v239, 53
	v_readlane_b32 s9, v239, 54
	v_readlane_b32 s12, v239, 57
	v_readlane_b32 s13, v239, 58
	v_readlane_b32 s14, v239, 59
	v_readlane_b32 s15, v239, 60
	v_readlane_b32 s16, v239, 61
	v_readlane_b32 s17, v239, 62
	v_readlane_b32 s18, v239, 63
	v_readlane_b32 s19, v238, 0
	s_waitcnt vmcnt(19) lgkmcnt(14)
	v_fma_f32 v148, v128, v148, v124
	v_fmac_f32_e32 v148, v127, v149
	v_fma_f32 v149, v128, v149, v124
	v_fmac_f32_e32 v149, v127, v150
	v_fmac_f32_e32 v148, v126, v150
	v_fmac_f32_e32 v149, v126, v151
	v_fmac_f32_e32 v148, v125, v151
	v_fmac_f32_e32 v149, v125, v108
	v_fmac_f32_e32 v148, v123, v108
	v_fmac_f32_e32 v149, v123, v109
	v_fmac_f32_e32 v148, v122, v109
	v_fmac_f32_e32 v149, v122, v106
	v_fmac_f32_e32 v148, v120, v106
	v_fmac_f32_e32 v149, v120, v107
	v_fmac_f32_e32 v148, v118, v107
	v_fmac_f32_e32 v149, v118, v104
	v_fmac_f32_e32 v148, v121, v104
	v_fmac_f32_e32 v149, v121, v105
	v_fmac_f32_e32 v148, v119, v105
	v_fmac_f32_e32 v149, v119, v102
	v_fmac_f32_e32 v148, v117, v102
	v_fmac_f32_e32 v149, v117, v103
	v_fmac_f32_e32 v148, v116, v103
	v_fmac_f32_e32 v149, v116, v100
	s_waitcnt vmcnt(18)
	v_fmac_f32_e32 v148, v147, v100
	v_fmac_f32_e32 v149, v147, v101
	s_waitcnt vmcnt(17)
	v_fmac_f32_e32 v148, v146, v101
	v_fmac_f32_e32 v149, v146, v98
	s_waitcnt vmcnt(16)
	v_fmac_f32_e32 v148, v144, v98
	v_fmac_f32_e32 v149, v144, v99
	s_waitcnt vmcnt(15)
	v_fmac_f32_e32 v148, v142, v99
	v_fmac_f32_e32 v149, v142, v96
	s_waitcnt vmcnt(14)
	v_fmac_f32_e32 v148, v140, v96
	v_fmac_f32_e32 v149, v140, v97
	s_waitcnt vmcnt(13)
	v_fmac_f32_e32 v148, v138, v97
	s_waitcnt lgkmcnt(13)
	v_fmac_f32_e32 v149, v138, v94
	s_waitcnt vmcnt(12)
	v_fmac_f32_e32 v148, v136, v94
	v_fmac_f32_e32 v149, v136, v95
	s_waitcnt vmcnt(11)
	v_fmac_f32_e32 v148, v133, v95
	s_waitcnt lgkmcnt(12)
	v_fmac_f32_e32 v149, v133, v92
	s_waitcnt vmcnt(10)
	v_fmac_f32_e32 v148, v145, v92
	v_fmac_f32_e32 v149, v145, v93
	s_waitcnt vmcnt(9)
	v_fmac_f32_e32 v148, v143, v93
	s_waitcnt lgkmcnt(11)
	v_fmac_f32_e32 v149, v143, v90
	s_waitcnt vmcnt(8)
	v_fmac_f32_e32 v148, v141, v90
	v_fmac_f32_e32 v149, v141, v91
	s_waitcnt vmcnt(7)
	v_fmac_f32_e32 v148, v139, v91
	s_waitcnt lgkmcnt(10)
	v_fmac_f32_e32 v149, v139, v88
	s_waitcnt vmcnt(6)
	v_fmac_f32_e32 v148, v137, v88
	v_fmac_f32_e32 v149, v137, v89
	s_waitcnt vmcnt(5)
	v_fmac_f32_e32 v148, v134, v89
	s_waitcnt lgkmcnt(9)
	v_fmac_f32_e32 v149, v134, v86
	s_waitcnt vmcnt(4)
	v_fmac_f32_e32 v148, v131, v86
	v_fmac_f32_e32 v149, v131, v87
	s_waitcnt vmcnt(3)
	v_fmac_f32_e32 v148, v129, v87
	s_waitcnt lgkmcnt(8)
	v_fmac_f32_e32 v149, v129, v84
	s_waitcnt vmcnt(2)
	v_fmac_f32_e32 v148, v135, v84
	v_fmac_f32_e32 v149, v135, v85
	s_waitcnt vmcnt(1)
	v_fmac_f32_e32 v148, v132, v85
	s_waitcnt lgkmcnt(7)
	v_fmac_f32_e32 v149, v132, v82
	s_waitcnt vmcnt(0)
	v_fmac_f32_e32 v148, v130, v82
	v_fmac_f32_e32 v149, v130, v83
	ds_write2st64_b32 v74, v148, v149 offset1:4
	v_fma_f32 v148, v128, v150, v124
	v_fmac_f32_e32 v148, v127, v151
	v_fma_f32 v149, v128, v151, v124
	v_fmac_f32_e32 v148, v126, v108
	v_fmac_f32_e32 v149, v127, v108
	v_fma_f32 v108, v128, v108, v124
	v_fmac_f32_e32 v148, v125, v109
	v_fmac_f32_e32 v149, v126, v109
	v_fmac_f32_e32 v108, v127, v109
	v_fma_f32 v109, v128, v109, v124
	v_fmac_f32_e32 v148, v123, v106
	v_fmac_f32_e32 v149, v125, v106
	v_fmac_f32_e32 v108, v126, v106
	v_fmac_f32_e32 v109, v127, v106
	v_fma_f32 v106, v128, v106, v124
	v_fmac_f32_e32 v148, v122, v107
	v_fmac_f32_e32 v149, v123, v107
	v_fmac_f32_e32 v108, v125, v107
	v_fmac_f32_e32 v109, v126, v107
	v_fmac_f32_e32 v106, v127, v107
	v_fma_f32 v107, v128, v107, v124
	v_fmac_f32_e32 v148, v120, v104
	v_fmac_f32_e32 v149, v122, v104
	v_fmac_f32_e32 v108, v123, v104
	v_fmac_f32_e32 v109, v125, v104
	v_fmac_f32_e32 v106, v126, v104
	v_fmac_f32_e32 v107, v127, v104
	v_fma_f32 v104, v128, v104, v124
	v_fmac_f32_e32 v148, v118, v105
	v_fmac_f32_e32 v149, v120, v105
	v_fmac_f32_e32 v108, v122, v105
	v_fmac_f32_e32 v109, v123, v105
	v_fmac_f32_e32 v106, v125, v105
	v_fmac_f32_e32 v107, v126, v105
	v_fmac_f32_e32 v104, v127, v105
	v_fma_f32 v105, v128, v105, v124
	v_fmac_f32_e32 v148, v121, v102
	v_fmac_f32_e32 v149, v118, v102
	v_fmac_f32_e32 v108, v120, v102
	v_fmac_f32_e32 v109, v122, v102
	v_fmac_f32_e32 v106, v123, v102
	v_fmac_f32_e32 v107, v125, v102
	v_fmac_f32_e32 v104, v126, v102
	v_fmac_f32_e32 v105, v127, v102
	v_fma_f32 v102, v128, v102, v124
	v_fmac_f32_e32 v148, v119, v103
	v_fmac_f32_e32 v149, v121, v103
	v_fmac_f32_e32 v108, v118, v103
	v_fmac_f32_e32 v109, v120, v103
	v_fmac_f32_e32 v106, v122, v103
	v_fmac_f32_e32 v107, v123, v103
	v_fmac_f32_e32 v104, v125, v103
	v_fmac_f32_e32 v105, v126, v103
	v_fmac_f32_e32 v102, v127, v103
	v_fma_f32 v103, v128, v103, v124
	v_fmac_f32_e32 v148, v117, v100
	v_fmac_f32_e32 v149, v119, v100
	v_fmac_f32_e32 v108, v121, v100
	v_fmac_f32_e32 v109, v118, v100
	v_fmac_f32_e32 v106, v120, v100
	v_fmac_f32_e32 v107, v122, v100
	v_fmac_f32_e32 v104, v123, v100
	v_fmac_f32_e32 v105, v125, v100
	v_fmac_f32_e32 v102, v126, v100
	v_fmac_f32_e32 v103, v127, v100
	v_fma_f32 v100, v128, v100, v124
	v_fmac_f32_e32 v148, v116, v101
	v_fmac_f32_e32 v149, v117, v101
	v_fmac_f32_e32 v108, v119, v101
	v_fmac_f32_e32 v109, v121, v101
	v_fmac_f32_e32 v106, v118, v101
	v_fmac_f32_e32 v107, v120, v101
	v_fmac_f32_e32 v104, v122, v101
	v_fmac_f32_e32 v105, v123, v101
	v_fmac_f32_e32 v102, v125, v101
	v_fmac_f32_e32 v103, v126, v101
	v_fmac_f32_e32 v100, v127, v101
	v_fma_f32 v101, v128, v101, v124
	v_fmac_f32_e32 v148, v147, v98
	v_fmac_f32_e32 v149, v116, v98
	v_fmac_f32_e32 v108, v117, v98
	v_fmac_f32_e32 v109, v119, v98
	v_fmac_f32_e32 v106, v121, v98
	v_fmac_f32_e32 v107, v118, v98
	v_fmac_f32_e32 v104, v120, v98
	v_fmac_f32_e32 v105, v122, v98
	v_fmac_f32_e32 v102, v123, v98
	v_fmac_f32_e32 v103, v125, v98
	v_fmac_f32_e32 v100, v126, v98
	v_fmac_f32_e32 v101, v127, v98
	v_fma_f32 v98, v128, v98, v124
	v_fmac_f32_e32 v124, v128, v99
	v_fmac_f32_e32 v98, v127, v99
	v_fmac_f32_e32 v124, v127, v96
	v_fmac_f32_e32 v101, v126, v99
	v_fmac_f32_e32 v98, v126, v96
	v_fmac_f32_e32 v124, v126, v97
	v_fmac_f32_e32 v100, v125, v99
	v_fmac_f32_e32 v101, v125, v96
	v_fmac_f32_e32 v98, v125, v97
	v_fmac_f32_e32 v124, v125, v94
	v_fmac_f32_e32 v103, v123, v99
	v_fmac_f32_e32 v100, v123, v96
	v_fmac_f32_e32 v101, v123, v97
	v_fmac_f32_e32 v98, v123, v94
	v_fmac_f32_e32 v124, v123, v95
	v_fmac_f32_e32 v102, v122, v99
	v_fmac_f32_e32 v103, v122, v96
	v_fmac_f32_e32 v100, v122, v97
	v_fmac_f32_e32 v101, v122, v94
	v_fmac_f32_e32 v98, v122, v95
	v_fmac_f32_e32 v124, v122, v92
	v_fmac_f32_e32 v105, v120, v99
	v_fmac_f32_e32 v102, v120, v96
	v_fmac_f32_e32 v103, v120, v97
	v_fmac_f32_e32 v100, v120, v94
	v_fmac_f32_e32 v101, v120, v95
	v_fmac_f32_e32 v98, v120, v92
	v_fmac_f32_e32 v124, v120, v93
	v_fmac_f32_e32 v104, v118, v99
	v_fmac_f32_e32 v105, v118, v96
	v_fmac_f32_e32 v102, v118, v97
	v_fmac_f32_e32 v103, v118, v94
	v_fmac_f32_e32 v100, v118, v95
	v_fmac_f32_e32 v101, v118, v92
	v_fmac_f32_e32 v98, v118, v93
	v_fmac_f32_e32 v124, v118, v90
	v_fmac_f32_e32 v107, v121, v99
	v_fmac_f32_e32 v104, v121, v96
	v_fmac_f32_e32 v105, v121, v97
	v_fmac_f32_e32 v102, v121, v94
	v_fmac_f32_e32 v103, v121, v95
	v_fmac_f32_e32 v100, v121, v92
	v_fmac_f32_e32 v101, v121, v93
	v_fmac_f32_e32 v98, v121, v90
	v_fmac_f32_e32 v124, v121, v91
	v_fmac_f32_e32 v106, v119, v99
	v_fmac_f32_e32 v107, v119, v96
	v_fmac_f32_e32 v104, v119, v97
	v_fmac_f32_e32 v105, v119, v94
	v_fmac_f32_e32 v102, v119, v95
	v_fmac_f32_e32 v103, v119, v92
	v_fmac_f32_e32 v100, v119, v93
	v_fmac_f32_e32 v101, v119, v90
	v_fmac_f32_e32 v98, v119, v91
	v_fmac_f32_e32 v124, v119, v88
	v_fmac_f32_e32 v109, v117, v99
	v_fmac_f32_e32 v106, v117, v96
	v_fmac_f32_e32 v107, v117, v97
	v_fmac_f32_e32 v104, v117, v94
	v_fmac_f32_e32 v105, v117, v95
	v_fmac_f32_e32 v102, v117, v92
	v_fmac_f32_e32 v103, v117, v93
	v_fmac_f32_e32 v100, v117, v90
	v_fmac_f32_e32 v101, v117, v91
	v_fmac_f32_e32 v98, v117, v88
	v_fmac_f32_e32 v124, v117, v89
	v_fmac_f32_e32 v108, v116, v99
	v_fmac_f32_e32 v109, v116, v96
	v_fmac_f32_e32 v106, v116, v97
	v_fmac_f32_e32 v107, v116, v94
	v_fmac_f32_e32 v104, v116, v95
	v_fmac_f32_e32 v105, v116, v92
	v_fmac_f32_e32 v102, v116, v93
	v_fmac_f32_e32 v103, v116, v90
	v_fmac_f32_e32 v100, v116, v91
	v_fmac_f32_e32 v101, v116, v88
	v_fmac_f32_e32 v98, v116, v89
	v_fmac_f32_e32 v124, v116, v86
	v_fmac_f32_e32 v149, v147, v99
	v_fmac_f32_e32 v108, v147, v96
	v_fmac_f32_e32 v109, v147, v97
	v_fmac_f32_e32 v106, v147, v94
	v_fmac_f32_e32 v107, v147, v95
	v_fmac_f32_e32 v104, v147, v92
	v_fmac_f32_e32 v105, v147, v93
	v_fmac_f32_e32 v102, v147, v90
	v_fmac_f32_e32 v103, v147, v91
	v_fmac_f32_e32 v100, v147, v88
	v_fmac_f32_e32 v101, v147, v89
	v_fmac_f32_e32 v98, v147, v86
	v_fmac_f32_e32 v124, v147, v87
	v_fmac_f32_e32 v148, v146, v99
	v_fmac_f32_e32 v149, v146, v96
	v_fmac_f32_e32 v108, v146, v97
	v_fmac_f32_e32 v109, v146, v94
	v_fmac_f32_e32 v106, v146, v95
	v_fmac_f32_e32 v107, v146, v92
	v_fmac_f32_e32 v104, v146, v93
	v_fmac_f32_e32 v105, v146, v90
	v_fmac_f32_e32 v102, v146, v91
	v_fmac_f32_e32 v103, v146, v88
	v_fmac_f32_e32 v100, v146, v89
	v_fmac_f32_e32 v101, v146, v86
	v_fmac_f32_e32 v98, v146, v87
	v_fmac_f32_e32 v124, v146, v84
	v_fmac_f32_e32 v148, v144, v96
	v_fmac_f32_e32 v149, v144, v97
	v_fmac_f32_e32 v108, v144, v94
	v_fmac_f32_e32 v109, v144, v95
	v_fmac_f32_e32 v106, v144, v92
	v_fmac_f32_e32 v107, v144, v93
	v_fmac_f32_e32 v104, v144, v90
	v_fmac_f32_e32 v105, v144, v91
	v_fmac_f32_e32 v102, v144, v88
	v_fmac_f32_e32 v103, v144, v89
	v_fmac_f32_e32 v100, v144, v86
	v_fmac_f32_e32 v101, v144, v87
	v_fmac_f32_e32 v98, v144, v84
	v_fmac_f32_e32 v124, v144, v85
	v_fmac_f32_e32 v148, v142, v97
	v_fmac_f32_e32 v149, v142, v94
	v_fmac_f32_e32 v108, v142, v95
	v_fmac_f32_e32 v109, v142, v92
	v_fmac_f32_e32 v106, v142, v93
	v_fmac_f32_e32 v107, v142, v90
	v_fmac_f32_e32 v104, v142, v91
	v_fmac_f32_e32 v105, v142, v88
	v_fmac_f32_e32 v102, v142, v89
	v_fmac_f32_e32 v103, v142, v86
	v_fmac_f32_e32 v100, v142, v87
	v_fmac_f32_e32 v101, v142, v84
	v_fmac_f32_e32 v98, v142, v85
	v_fmac_f32_e32 v124, v142, v82
	v_fmac_f32_e32 v148, v140, v94
	v_fmac_f32_e32 v149, v140, v95
	v_fmac_f32_e32 v108, v140, v92
	v_fmac_f32_e32 v109, v140, v93
	v_fmac_f32_e32 v106, v140, v90
	v_fmac_f32_e32 v107, v140, v91
	v_fmac_f32_e32 v104, v140, v88
	v_fmac_f32_e32 v105, v140, v89
	v_fmac_f32_e32 v102, v140, v86
	v_fmac_f32_e32 v103, v140, v87
	v_fmac_f32_e32 v100, v140, v84
	v_fmac_f32_e32 v101, v140, v85
	v_fmac_f32_e32 v98, v140, v82
	v_fmac_f32_e32 v124, v140, v83
	v_fmac_f32_e32 v148, v138, v95
	v_fmac_f32_e32 v149, v138, v92
	v_fmac_f32_e32 v108, v138, v93
	v_fmac_f32_e32 v109, v138, v90
	v_fmac_f32_e32 v106, v138, v91
	v_fmac_f32_e32 v107, v138, v88
	v_fmac_f32_e32 v104, v138, v89
	v_fmac_f32_e32 v105, v138, v86
	v_fmac_f32_e32 v102, v138, v87
	v_fmac_f32_e32 v103, v138, v84
	v_fmac_f32_e32 v100, v138, v85
	v_fmac_f32_e32 v101, v138, v82
	v_fmac_f32_e32 v98, v138, v83
	s_waitcnt lgkmcnt(7)
	v_fmac_f32_e32 v124, v138, v80
	v_fmac_f32_e32 v148, v136, v92
	v_fmac_f32_e32 v149, v136, v93
	v_fmac_f32_e32 v108, v136, v90
	v_fmac_f32_e32 v109, v136, v91
	v_fmac_f32_e32 v106, v136, v88
	v_fmac_f32_e32 v107, v136, v89
	v_fmac_f32_e32 v104, v136, v86
	v_fmac_f32_e32 v105, v136, v87
	v_fmac_f32_e32 v102, v136, v84
	v_fmac_f32_e32 v103, v136, v85
	v_fmac_f32_e32 v100, v136, v82
	v_fmac_f32_e32 v101, v136, v83
	v_fmac_f32_e32 v98, v136, v80
	v_fmac_f32_e32 v124, v136, v81
	v_fmac_f32_e32 v148, v133, v93
	v_fmac_f32_e32 v149, v133, v90
	v_fmac_f32_e32 v108, v133, v91
	v_fmac_f32_e32 v109, v133, v88
	v_fmac_f32_e32 v106, v133, v89
	v_fmac_f32_e32 v107, v133, v86
	v_fmac_f32_e32 v104, v133, v87
	v_fmac_f32_e32 v105, v133, v84
	v_fmac_f32_e32 v102, v133, v85
	v_fmac_f32_e32 v103, v133, v82
	v_fmac_f32_e32 v100, v133, v83
	v_fmac_f32_e32 v101, v133, v80
	v_fmac_f32_e32 v98, v133, v81
	s_waitcnt lgkmcnt(6)
	v_fmac_f32_e32 v124, v133, v78
	v_fmac_f32_e32 v148, v145, v90
	v_fmac_f32_e32 v149, v145, v91
	v_fmac_f32_e32 v108, v145, v88
	v_fmac_f32_e32 v109, v145, v89
	v_fmac_f32_e32 v106, v145, v86
	v_fmac_f32_e32 v107, v145, v87
	v_fmac_f32_e32 v104, v145, v84
	v_fmac_f32_e32 v105, v145, v85
	v_fmac_f32_e32 v102, v145, v82
	v_fmac_f32_e32 v103, v145, v83
	v_fmac_f32_e32 v100, v145, v80
	v_fmac_f32_e32 v101, v145, v81
	v_fmac_f32_e32 v98, v145, v78
	v_fmac_f32_e32 v124, v145, v79
	v_fmac_f32_e32 v148, v143, v91
	v_fmac_f32_e32 v149, v143, v88
	v_fmac_f32_e32 v108, v143, v89
	v_fmac_f32_e32 v109, v143, v86
	v_fmac_f32_e32 v106, v143, v87
	v_fmac_f32_e32 v107, v143, v84
	v_fmac_f32_e32 v104, v143, v85
	v_fmac_f32_e32 v105, v143, v82
	v_fmac_f32_e32 v102, v143, v83
	v_fmac_f32_e32 v103, v143, v80
	v_fmac_f32_e32 v100, v143, v81
	v_fmac_f32_e32 v101, v143, v78
	v_fmac_f32_e32 v98, v143, v79
	s_waitcnt lgkmcnt(5)
	v_fmac_f32_e32 v124, v143, v76
	v_fmac_f32_e32 v148, v141, v88
	v_fmac_f32_e32 v149, v141, v89
	v_fmac_f32_e32 v108, v141, v86
	v_fmac_f32_e32 v109, v141, v87
	v_fmac_f32_e32 v106, v141, v84
	v_fmac_f32_e32 v107, v141, v85
	v_fmac_f32_e32 v104, v141, v82
	v_fmac_f32_e32 v105, v141, v83
	v_fmac_f32_e32 v102, v141, v80
	v_fmac_f32_e32 v103, v141, v81
	v_fmac_f32_e32 v100, v141, v78
	v_fmac_f32_e32 v101, v141, v79
	v_fmac_f32_e32 v98, v141, v76
	v_fmac_f32_e32 v124, v141, v77
	v_fmac_f32_e32 v148, v139, v89
	v_fmac_f32_e32 v149, v139, v86
	v_fmac_f32_e32 v108, v139, v87
	v_fmac_f32_e32 v109, v139, v84
	v_fmac_f32_e32 v106, v139, v85
	v_fmac_f32_e32 v107, v139, v82
	v_fmac_f32_e32 v104, v139, v83
	v_fmac_f32_e32 v105, v139, v80
	v_fmac_f32_e32 v102, v139, v81
	v_fmac_f32_e32 v103, v139, v78
	v_fmac_f32_e32 v100, v139, v79
	v_fmac_f32_e32 v101, v139, v76
	v_fmac_f32_e32 v98, v139, v77
	s_waitcnt lgkmcnt(4)
	v_fmac_f32_e32 v124, v139, v72
	v_fmac_f32_e32 v148, v137, v86
	v_fmac_f32_e32 v149, v137, v87
	v_fmac_f32_e32 v108, v137, v84
	v_fmac_f32_e32 v109, v137, v85
	v_fmac_f32_e32 v106, v137, v82
	v_fmac_f32_e32 v107, v137, v83
	v_fmac_f32_e32 v104, v137, v80
	v_fmac_f32_e32 v105, v137, v81
	v_fmac_f32_e32 v102, v137, v78
	v_fmac_f32_e32 v103, v137, v79
	v_fmac_f32_e32 v100, v137, v76
	v_fmac_f32_e32 v101, v137, v77
	v_fmac_f32_e32 v98, v137, v72
	v_fmac_f32_e32 v124, v137, v73
	v_fmac_f32_e32 v148, v134, v87
	v_fmac_f32_e32 v149, v134, v84
	v_fmac_f32_e32 v108, v134, v85
	v_fmac_f32_e32 v109, v134, v82
	v_fmac_f32_e32 v106, v134, v83
	v_fmac_f32_e32 v107, v134, v80
	v_fmac_f32_e32 v104, v134, v81
	v_fmac_f32_e32 v105, v134, v78
	v_fmac_f32_e32 v102, v134, v79
	v_fmac_f32_e32 v103, v134, v76
	v_fmac_f32_e32 v100, v134, v77
	v_fmac_f32_e32 v101, v134, v72
	v_fmac_f32_e32 v98, v134, v73
	s_waitcnt lgkmcnt(3)
	v_fmac_f32_e32 v124, v134, v70
	v_fmac_f32_e32 v148, v131, v84
	v_fmac_f32_e32 v149, v131, v85
	v_fmac_f32_e32 v108, v131, v82
	v_fmac_f32_e32 v109, v131, v83
	v_fmac_f32_e32 v106, v131, v80
	v_fmac_f32_e32 v107, v131, v81
	v_fmac_f32_e32 v104, v131, v78
	v_fmac_f32_e32 v105, v131, v79
	v_fmac_f32_e32 v102, v131, v76
	v_fmac_f32_e32 v103, v131, v77
	v_fmac_f32_e32 v100, v131, v72
	v_fmac_f32_e32 v101, v131, v73
	v_fmac_f32_e32 v98, v131, v70
	v_fmac_f32_e32 v124, v131, v71
	v_fmac_f32_e32 v148, v129, v85
	v_fmac_f32_e32 v149, v129, v82
	v_fmac_f32_e32 v108, v129, v83
	v_fmac_f32_e32 v109, v129, v80
	v_fmac_f32_e32 v106, v129, v81
	v_fmac_f32_e32 v107, v129, v78
	v_fmac_f32_e32 v104, v129, v79
	v_fmac_f32_e32 v105, v129, v76
	v_fmac_f32_e32 v102, v129, v77
	v_fmac_f32_e32 v103, v129, v72
	v_fmac_f32_e32 v100, v129, v73
	v_fmac_f32_e32 v101, v129, v70
	v_fmac_f32_e32 v98, v129, v71
	s_waitcnt lgkmcnt(2)
	v_fmac_f32_e32 v124, v129, v68
	v_fmac_f32_e32 v148, v135, v82
	v_fmac_f32_e32 v149, v135, v83
	v_fmac_f32_e32 v108, v135, v80
	v_fmac_f32_e32 v109, v135, v81
	v_fmac_f32_e32 v106, v135, v78
	v_fmac_f32_e32 v107, v135, v79
	v_fmac_f32_e32 v104, v135, v76
	v_fmac_f32_e32 v105, v135, v77
	v_fmac_f32_e32 v102, v135, v72
	v_fmac_f32_e32 v103, v135, v73
	v_fmac_f32_e32 v100, v135, v70
	v_fmac_f32_e32 v101, v135, v71
	v_fmac_f32_e32 v98, v135, v68
	v_fmac_f32_e32 v124, v135, v69
	v_fmac_f32_e32 v148, v132, v83
	v_fmac_f32_e32 v149, v132, v80
	v_fmac_f32_e32 v108, v132, v81
	v_fmac_f32_e32 v109, v132, v78
	v_fmac_f32_e32 v106, v132, v79
	v_fmac_f32_e32 v107, v132, v76
	v_fmac_f32_e32 v104, v132, v77
	v_fmac_f32_e32 v105, v132, v72
	v_fmac_f32_e32 v102, v132, v73
	v_fmac_f32_e32 v103, v132, v70
	v_fmac_f32_e32 v100, v132, v71
	v_fmac_f32_e32 v101, v132, v68
	v_fmac_f32_e32 v98, v132, v69
	s_waitcnt lgkmcnt(1)
	v_fmac_f32_e32 v124, v132, v66
	v_fmac_f32_e32 v148, v130, v80
	v_fmac_f32_e32 v149, v130, v81
	v_fmac_f32_e32 v108, v130, v78
	v_fmac_f32_e32 v109, v130, v79
	v_fmac_f32_e32 v106, v130, v76
	v_fmac_f32_e32 v107, v130, v77
	v_fmac_f32_e32 v104, v130, v72
	v_fmac_f32_e32 v105, v130, v73
	v_fmac_f32_e32 v102, v130, v70
	v_fmac_f32_e32 v103, v130, v71
	v_fmac_f32_e32 v100, v130, v68
	v_fmac_f32_e32 v101, v130, v69
	v_fmac_f32_e32 v98, v130, v66
	v_fmac_f32_e32 v124, v130, v67
	ds_write2st64_b32 v74, v148, v149 offset0:8 offset1:12
	ds_write2st64_b32 v74, v108, v109 offset0:16 offset1:20
	ds_write2st64_b32 v74, v106, v107 offset0:24 offset1:28
	ds_write2st64_b32 v74, v104, v105 offset0:32 offset1:36
	ds_write2st64_b32 v74, v102, v103 offset0:40 offset1:44
	ds_write2st64_b32 v74, v100, v101 offset0:48 offset1:52
	ds_write2st64_b32 v74, v98, v124 offset0:56 offset1:60
	v_lshlrev_b32_e32 v74, 2, v115
	v_add_u32_e32 v86, s40, v74
	v_lshl_add_u32 v88, v113, 12, v86
	s_waitcnt lgkmcnt(0)
	s_barrier
	global_load_dwordx4 v[66:69], v74, s[4:5] offset:1024
	global_load_dwordx4 v[70:73], v74, s[6:7] offset:1024
	ds_read_b128 v[78:81], v88
	v_and_b32_e32 v74, 64, v110
	v_add_u32_e32 v74, 64, v74
	v_xor_b32_e32 v76, 1, v110
	v_cmp_lt_i32_e32 vcc, v76, v74
	s_waitcnt lgkmcnt(0)
	v_mov_b32_e32 v77, v80
	v_mov_b32_e32 v82, v78
	v_cndmask_b32_e32 v76, v110, v76, vcc
	v_lshlrev_b32_e32 v89, 2, v76
	v_mov_b32_e32 v76, v79
	v_mov_b32_e32 v83, v81
	v_pk_add_f32 v[76:77], v[76:77], v[82:83]
	v_xor_b32_e32 v82, 2, v110
	v_add_f32_e32 v76, v76, v77
	v_cmp_lt_i32_e32 vcc, v82, v74
	v_lshl_or_b32 v87, v113, 2, 1
	s_waitcnt lgkmcnt(0)
	s_nop 1
	v_add_f32_dpp v76, v76, v76 quad_perm:[1,0,3,2] row_mask:0xf bank_mask:0xf
	v_cndmask_b32_e32 v82, v110, v82, vcc
	v_lshlrev_b32_e32 v90, 2, v82
	v_xor_b32_e32 v82, 4, v110
	v_cmp_lt_i32_e32 vcc, v82, v74
	s_waitcnt lgkmcnt(0)
	s_nop 1
	v_add_f32_dpp v76, v76, v76 quad_perm:[2,3,0,1] row_mask:0xf bank_mask:0xf
	v_cndmask_b32_e32 v82, v110, v82, vcc
	v_lshlrev_b32_e32 v91, 2, v82
	v_xor_b32_e32 v82, 8, v110
	v_cmp_lt_i32_e32 vcc, v82, v74
	s_waitcnt lgkmcnt(0)
	s_nop 1
	v_add_f32_dpp v76, v76, v76 row_half_mirror row_mask:0xf bank_mask:0xf
	v_cndmask_b32_e32 v82, v110, v82, vcc
	v_lshlrev_b32_e32 v92, 2, v82
	v_xor_b32_e32 v82, 16, v110
	v_cmp_lt_i32_e32 vcc, v82, v74
	s_waitcnt lgkmcnt(0)
	s_nop 1
	v_add_f32_dpp v76, v76, v76 row_mirror row_mask:0xf bank_mask:0xf
	v_cndmask_b32_e32 v82, v110, v82, vcc
	v_lshlrev_b32_e32 v93, 2, v82
	v_xor_b32_e32 v82, 32, v110
	v_cmp_lt_i32_e32 vcc, v82, v74
	s_nop 1
	v_cndmask_b32_e32 v74, v110, v82, vcc
	v_lshlrev_b32_e32 v94, 2, v74
	s_waitcnt lgkmcnt(0)
	v_mov_b32_e32 v77, v76
	v_mov_b32_e32 v254, v76
	s_nop 1
	v_permlane16_swap_b32 v77, v254
	v_add_f32_e32 v74, v77, v254
	s_waitcnt lgkmcnt(0)
	v_mov_b32_e32 v76, v74
	v_mov_b32_e32 v254, v74
	s_nop 1
	v_permlane32_swap_b32 v76, v254
	v_add_f32_e32 v74, v76, v254
	v_fmamk_f32 v83, v74, 0xbb800000, v79
	v_fmamk_f32 v82, v74, 0xbb800000, v78
	v_fmamk_f32 v81, v74, 0xbb800000, v81
	v_fmac_f32_e32 v80, 0xbb800000, v74
	v_pk_mul_f32 v[76:77], v[80:81], v[80:81]
	v_pk_mul_f32 v[78:79], v[82:83], v[82:83]
	s_nop 0
	v_pk_mov_b32 v[84:85], v[78:79], v[76:77] op_sel:[1,0]
	v_mov_b32_e32 v79, v77
	v_pk_add_f32 v[76:77], v[84:85], v[78:79]
	s_waitcnt vmcnt(0)
	v_mov_b32_e32 v78, v70
	v_add_f32_e32 v74, v76, v77
	v_mov_b32_e32 v77, v80
	v_mov_b32_e32 v79, v72
	v_mov_b32_e32 v80, v83
	v_mov_b32_e32 v72, v71
	s_waitcnt lgkmcnt(0)
	s_nop 1
	v_add_f32_dpp v74, v74, v74 quad_perm:[1,0,3,2] row_mask:0xf bank_mask:0xf
	s_waitcnt lgkmcnt(0)
	s_nop 1
	v_add_f32_dpp v74, v74, v74 quad_perm:[2,3,0,1] row_mask:0xf bank_mask:0xf
	s_waitcnt lgkmcnt(0)
	s_nop 1
	v_add_f32_dpp v74, v74, v74 row_half_mirror row_mask:0xf bank_mask:0xf
	s_waitcnt lgkmcnt(0)
	s_nop 1
	v_add_f32_dpp v74, v74, v74 row_mirror row_mask:0xf bank_mask:0xf
	s_waitcnt lgkmcnt(0)
	v_mov_b32_e32 v76, v74
	v_mov_b32_e32 v254, v74
	s_nop 1
	v_permlane16_swap_b32 v76, v254
	v_add_f32_e32 v74, v76, v254
	s_waitcnt lgkmcnt(0)
	v_mov_b32_e32 v76, v74
	v_mov_b32_e32 v254, v74
	s_nop 1
	v_permlane32_swap_b32 v76, v254
	v_add_f32_e32 v74, v76, v254
	v_fmamk_f32 v74, v74, 0x3b800000, v111
	v_mul_f32_e32 v76, 0x4b800000, v74
	v_cmp_gt_f32_e32 vcc, s42, v74
	s_nop 1
	v_cndmask_b32_e32 v74, v74, v76, vcc
	v_rsq_f32_e32 v74, v74
	s_nop 0
	v_mul_f32_e32 v76, 0x45800000, v74
	v_cndmask_b32_e32 v74, v74, v76, vcc
	v_mov_b32_e32 v76, v82
	v_pk_mul_f32 v[84:85], v[76:77], v[74:75] op_sel_hi:[1,0]
	v_mov_b32_e32 v76, v66
	v_mov_b32_e32 v77, v68
	v_pk_fma_f32 v[84:85], v[76:77], v[84:85], v[78:79]
	v_pk_mul_f32 v[80:81], v[80:81], v[74:75] op_sel_hi:[1,0]
	v_mul_f32_e32 v66, 0xbfb8aa3b, v84
	v_mov_b32_e32 v68, v67
	v_exp_f32_e32 v70, v66
	v_pk_fma_f32 v[66:67], v[68:69], v[80:81], v[72:73]
	v_mul_f32_e32 v74, 0xbfb8aa3b, v85
	v_mul_f32_e32 v71, 0xbfb8aa3b, v66
	v_exp_f32_e32 v71, v71
	v_exp_f32_e32 v74, v74
	v_mul_f32_e32 v80, 0xbfb8aa3b, v67
	v_exp_f32_e32 v81, v80
	v_add_f32_e32 v71, 1.0, v71
	v_add_f32_e32 v70, 1.0, v70
	v_rcp_f32_e32 v80, v71
	v_add_f32_e32 v71, 1.0, v74
	v_rcp_f32_e32 v70, v70
	v_rcp_f32_e32 v71, v71
	v_add_f32_e32 v74, 1.0, v81
	v_rcp_f32_e32 v81, v74
	v_lshl_add_u32 v74, v115, 1, s41
	v_pk_mul_f32 v[70:71], v[84:85], v[70:71]
	v_pk_mul_f32 v[66:67], v[66:67], v[80:81]
	v_and_b32_sdwa v80, v71, v112 dst_sel:DWORD dst_unused:UNUSED_PAD src0_sel:WORD_1 src1_sel:DWORD
	v_and_b32_sdwa v81, v70, v112 dst_sel:DWORD dst_unused:UNUSED_PAD src0_sel:WORD_1 src1_sel:DWORD
	v_add3_u32 v70, v70, v81, s43
	v_add3_u32 v71, v71, v80, s43
	v_and_b32_sdwa v80, v67, v112 dst_sel:DWORD dst_unused:UNUSED_PAD src0_sel:WORD_1 src1_sel:DWORD
	v_and_b32_sdwa v81, v66, v112 dst_sel:DWORD dst_unused:UNUSED_PAD src0_sel:WORD_1 src1_sel:DWORD
	v_add3_u32 v67, v67, v80, s43
	v_add3_u32 v66, v66, v81, s43
	v_and_b32_e32 v67, 0xffff0000, v67
	v_and_b32_e32 v66, 0xffff0000, v66
	v_or_b32_sdwa v67, v67, v71 dst_sel:DWORD dst_unused:UNUSED_PAD src0_sel:DWORD src1_sel:WORD_1
	v_or_b32_sdwa v66, v66, v70 dst_sel:DWORD dst_unused:UNUSED_PAD src0_sel:DWORD src1_sel:WORD_1
	v_mad_u64_u32 v[70:71], s[4:5], v113, s44, v[74:75]
	ds_write_b64 v70, v[66:67]
	v_lshl_add_u32 v66, v87, 10, v86
	ds_read_b128 v[80:83], v66
	s_waitcnt lgkmcnt(0)
	v_mov_b32_e32 v66, v81
	v_mov_b32_e32 v67, v82
	v_mov_b32_e32 v70, v80
	v_mov_b32_e32 v71, v83
	v_pk_add_f32 v[66:67], v[66:67], v[70:71]
	s_nop 0
	v_add_f32_e32 v66, v66, v67
	s_waitcnt lgkmcnt(0)
	s_nop 1
	v_add_f32_dpp v66, v66, v66 quad_perm:[1,0,3,2] row_mask:0xf bank_mask:0xf
	s_waitcnt lgkmcnt(0)
	s_nop 1
	v_add_f32_dpp v66, v66, v66 quad_perm:[2,3,0,1] row_mask:0xf bank_mask:0xf
	s_waitcnt lgkmcnt(0)
	s_nop 1
	v_add_f32_dpp v66, v66, v66 row_half_mirror row_mask:0xf bank_mask:0xf
	s_waitcnt lgkmcnt(0)
	s_nop 1
	v_add_f32_dpp v66, v66, v66 row_mirror row_mask:0xf bank_mask:0xf
	s_waitcnt lgkmcnt(0)
	v_mov_b32_e32 v67, v66
	v_mov_b32_e32 v254, v66
	s_nop 1
	v_permlane16_swap_b32 v67, v254
	v_add_f32_e32 v66, v67, v254
	s_waitcnt lgkmcnt(0)
	v_mov_b32_e32 v67, v66
	v_mov_b32_e32 v254, v66
	s_nop 1
	v_permlane32_swap_b32 v67, v254
	v_add_f32_e32 v70, v67, v254
	v_fmamk_f32 v67, v70, 0xbb800000, v81
	v_fmamk_f32 v66, v70, 0xbb800000, v80
	v_fmamk_f32 v83, v70, 0xbb800000, v83
	v_fmac_f32_e32 v82, 0xbb800000, v70
	v_pk_mul_f32 v[70:71], v[82:83], v[82:83]
	v_pk_mul_f32 v[80:81], v[66:67], v[66:67]
	s_nop 0
	v_pk_mov_b32 v[84:85], v[80:81], v[70:71] op_sel:[1,0]
	v_mov_b32_e32 v81, v71
	v_pk_add_f32 v[70:71], v[84:85], v[80:81]
	v_mov_b32_e32 v80, v66
	v_add_f32_e32 v70, v70, v71
	v_mov_b32_e32 v81, v82
	v_mov_b32_e32 v82, v67
	s_waitcnt lgkmcnt(0)
	s_nop 1
	v_add_f32_dpp v70, v70, v70 quad_perm:[1,0,3,2] row_mask:0xf bank_mask:0xf
	s_waitcnt lgkmcnt(0)
	s_nop 1
	v_add_f32_dpp v70, v70, v70 quad_perm:[2,3,0,1] row_mask:0xf bank_mask:0xf
	s_waitcnt lgkmcnt(0)
	s_nop 1
	v_add_f32_dpp v70, v70, v70 row_half_mirror row_mask:0xf bank_mask:0xf
	s_waitcnt lgkmcnt(0)
	s_nop 1
	v_add_f32_dpp v70, v70, v70 row_mirror row_mask:0xf bank_mask:0xf
	s_waitcnt lgkmcnt(0)
	v_mov_b32_e32 v71, v70
	v_mov_b32_e32 v254, v70
	s_nop 1
	v_permlane16_swap_b32 v71, v254
	v_add_f32_e32 v70, v71, v254
	s_waitcnt lgkmcnt(0)
	v_mov_b32_e32 v71, v70
	v_mov_b32_e32 v254, v70
	s_nop 1
	v_permlane32_swap_b32 v71, v254
	v_add_f32_e32 v70, v71, v254
	v_fmamk_f32 v70, v70, 0x3b800000, v111
	v_mul_f32_e32 v71, 0x4b800000, v70
	v_cmp_gt_f32_e32 vcc, s42, v70
	s_nop 1
	v_cndmask_b32_e32 v70, v70, v71, vcc
	v_rsq_f32_e32 v70, v70
	s_nop 0
	v_mul_f32_e32 v71, 0x45800000, v70
	v_cndmask_b32_e32 v70, v70, v71, vcc
	v_pk_mul_f32 v[80:81], v[80:81], v[70:71] op_sel_hi:[1,0]
	s_nop 0
	v_pk_fma_f32 v[80:81], v[76:77], v[80:81], v[78:79]
	s_nop 0
	v_mul_f32_e32 v66, 0xbfb8aa3b, v80
	v_exp_f32_e32 v71, v66
	s_nop 0
	v_pk_mul_f32 v[66:67], v[82:83], v[70:71] op_sel_hi:[1,0]
	s_nop 0
	v_pk_fma_f32 v[66:67], v[68:69], v[66:67], v[72:73]
	s_nop 0
	v_mul_f32_e32 v70, 0xbfb8aa3b, v66
	v_exp_f32_e32 v82, v70
	v_add_f32_e32 v70, 1.0, v71
	v_rcp_f32_e32 v70, v70
	v_add_f32_e32 v71, 1.0, v82
	v_mul_f32_e32 v82, 0xbfb8aa3b, v81
	v_exp_f32_e32 v83, v82
	v_mul_f32_e32 v82, 0xbfb8aa3b, v67
	v_exp_f32_e32 v84, v82
	v_rcp_f32_e32 v82, v71
	v_add_f32_e32 v71, 1.0, v83
	v_rcp_f32_e32 v71, v71
	v_add_f32_e32 v83, 1.0, v84
	v_rcp_f32_e32 v83, v83
	v_pk_mul_f32 v[70:71], v[80:81], v[70:71]
	s_nop 0
	v_and_b32_sdwa v80, v71, v112 dst_sel:DWORD dst_unused:UNUSED_PAD src0_sel:WORD_1 src1_sel:DWORD
	v_pk_mul_f32 v[66:67], v[66:67], v[82:83]
	v_and_b32_sdwa v81, v70, v112 dst_sel:DWORD dst_unused:UNUSED_PAD src0_sel:WORD_1 src1_sel:DWORD
	v_add3_u32 v70, v70, v81, s43
	v_add3_u32 v71, v71, v80, s43
	v_and_b32_sdwa v80, v67, v112 dst_sel:DWORD dst_unused:UNUSED_PAD src0_sel:WORD_1 src1_sel:DWORD
	v_and_b32_sdwa v81, v66, v112 dst_sel:DWORD dst_unused:UNUSED_PAD src0_sel:WORD_1 src1_sel:DWORD
	v_add3_u32 v67, v67, v80, s43
	v_add3_u32 v66, v66, v81, s43
	v_and_b32_e32 v67, 0xffff0000, v67
	v_and_b32_e32 v66, 0xffff0000, v66
	v_or_b32_sdwa v67, v67, v71 dst_sel:DWORD dst_unused:UNUSED_PAD src0_sel:DWORD src1_sel:WORD_1
	v_or_b32_sdwa v66, v66, v70 dst_sel:DWORD dst_unused:UNUSED_PAD src0_sel:DWORD src1_sel:WORD_1
	v_mad_u64_u32 v[70:71], s[4:5], v87, s45, v[74:75]
	ds_write_b64 v70, v[66:67]
	ds_read_b128 v[80:83], v88 offset:2048
	s_waitcnt lgkmcnt(0)
	v_mov_b32_e32 v66, v81
	v_mov_b32_e32 v67, v82
	v_mov_b32_e32 v84, v80
	v_mov_b32_e32 v85, v83
	v_pk_add_f32 v[66:67], v[66:67], v[84:85]
	s_nop 0
	v_add_f32_e32 v66, v66, v67
	s_waitcnt lgkmcnt(0)
	s_nop 1
	v_add_f32_dpp v66, v66, v66 quad_perm:[1,0,3,2] row_mask:0xf bank_mask:0xf
	s_waitcnt lgkmcnt(0)
	s_nop 1
	v_add_f32_dpp v66, v66, v66 quad_perm:[2,3,0,1] row_mask:0xf bank_mask:0xf
	s_waitcnt lgkmcnt(0)
	s_nop 1
	v_add_f32_dpp v66, v66, v66 row_half_mirror row_mask:0xf bank_mask:0xf
	s_waitcnt lgkmcnt(0)
	s_nop 1
	v_add_f32_dpp v66, v66, v66 row_mirror row_mask:0xf bank_mask:0xf
	s_waitcnt lgkmcnt(0)
	v_mov_b32_e32 v67, v66
	v_mov_b32_e32 v254, v66
	s_nop 1
	v_permlane16_swap_b32 v67, v254
	v_add_f32_e32 v66, v67, v254
	s_waitcnt lgkmcnt(0)
	v_mov_b32_e32 v67, v66
	v_mov_b32_e32 v254, v66
	s_nop 1
	v_permlane32_swap_b32 v67, v254
	v_add_f32_e32 v71, v67, v254
	v_fmamk_f32 v67, v71, 0xbb800000, v81
	v_fmamk_f32 v66, v71, 0xbb800000, v80
	v_fmamk_f32 v83, v71, 0xbb800000, v83
	v_fmac_f32_e32 v82, 0xbb800000, v71
	v_pk_mul_f32 v[80:81], v[82:83], v[82:83]
	v_pk_mul_f32 v[84:85], v[66:67], v[66:67]
	s_nop 0
	v_pk_mov_b32 v[86:87], v[84:85], v[80:81] op_sel:[1,0]
	v_mov_b32_e32 v85, v81
	v_pk_add_f32 v[80:81], v[86:87], v[84:85]
	s_nop 0
	v_add_f32_e32 v71, v80, v81
	v_mov_b32_e32 v80, v66
	v_mov_b32_e32 v81, v82
	v_mov_b32_e32 v82, v67
	s_waitcnt lgkmcnt(0)
	s_nop 1
	v_add_f32_dpp v71, v71, v71 quad_perm:[1,0,3,2] row_mask:0xf bank_mask:0xf
	s_waitcnt lgkmcnt(0)
	s_nop 1
	v_add_f32_dpp v71, v71, v71 quad_perm:[2,3,0,1] row_mask:0xf bank_mask:0xf
	s_waitcnt lgkmcnt(0)
	s_nop 1
	v_add_f32_dpp v71, v71, v71 row_half_mirror row_mask:0xf bank_mask:0xf
	s_waitcnt lgkmcnt(0)
	s_nop 1
	v_add_f32_dpp v71, v71, v71 row_mirror row_mask:0xf bank_mask:0xf
	s_waitcnt lgkmcnt(0)
	v_mov_b32_e32 v74, v71
	v_mov_b32_e32 v254, v71
	s_nop 1
	v_permlane16_swap_b32 v74, v254
	v_add_f32_e32 v71, v74, v254
	s_waitcnt lgkmcnt(0)
	v_mov_b32_e32 v74, v71
	v_mov_b32_e32 v254, v71
	s_nop 1
	v_permlane32_swap_b32 v74, v254
	v_add_f32_e32 v71, v74, v254
	v_fmamk_f32 v71, v71, 0x3b800000, v111
	v_mul_f32_e32 v74, 0x4b800000, v71
	v_cmp_gt_f32_e32 vcc, s42, v71
	s_nop 1
	v_cndmask_b32_e32 v71, v71, v74, vcc
	v_rsq_f32_e32 v71, v71
	s_nop 0
	v_mul_f32_e32 v74, 0x45800000, v71
	v_cndmask_b32_e32 v74, v71, v74, vcc
	v_pk_mul_f32 v[80:81], v[80:81], v[74:75] op_sel_hi:[1,0]
	s_nop 0
	v_pk_fma_f32 v[80:81], v[76:77], v[80:81], v[78:79]
	s_nop 0
	v_mul_f32_e32 v66, 0xbfb8aa3b, v80
	v_exp_f32_e32 v71, v66
	v_pk_mul_f32 v[66:67], v[82:83], v[74:75] op_sel_hi:[1,0]
	v_add_f32_e32 v71, 1.0, v71
	v_pk_fma_f32 v[66:67], v[68:69], v[66:67], v[72:73]
	v_rcp_f32_e32 v82, v71
	v_mul_f32_e32 v74, 0xbfb8aa3b, v66
	v_exp_f32_e32 v74, v74
	v_mul_f32_e32 v83, 0xbfb8aa3b, v67
	v_exp_f32_e32 v85, v83
	v_add_f32_e32 v71, 1.0, v74
	v_mul_f32_e32 v74, 0xbfb8aa3b, v81
	v_exp_f32_e32 v74, v74
	v_rcp_f32_e32 v84, v71
	v_add_f32_e32 v71, 1.0, v74
	v_rcp_f32_e32 v83, v71
	v_add_f32_e32 v71, 1.0, v85
	v_rcp_f32_e32 v85, v71
	v_pk_mul_f32 v[80:81], v[80:81], v[82:83]
	s_nop 0
	v_and_b32_sdwa v71, v81, v112 dst_sel:DWORD dst_unused:UNUSED_PAD src0_sel:WORD_1 src1_sel:DWORD
	v_pk_mul_f32 v[66:67], v[66:67], v[84:85]
	v_and_b32_sdwa v74, v80, v112 dst_sel:DWORD dst_unused:UNUSED_PAD src0_sel:WORD_1 src1_sel:DWORD
	v_add3_u32 v74, v80, v74, s43
	v_add3_u32 v71, v81, v71, s43
	v_and_b32_sdwa v80, v67, v112 dst_sel:DWORD dst_unused:UNUSED_PAD src0_sel:WORD_1 src1_sel:DWORD
	v_and_b32_sdwa v81, v66, v112 dst_sel:DWORD dst_unused:UNUSED_PAD src0_sel:WORD_1 src1_sel:DWORD
	v_add3_u32 v67, v67, v80, s43
	v_add3_u32 v66, v66, v81, s43
	v_and_b32_e32 v67, 0xffff0000, v67
	v_and_b32_e32 v66, 0xffff0000, v66
	v_or_b32_sdwa v67, v67, v71 dst_sel:DWORD dst_unused:UNUSED_PAD src0_sel:DWORD src1_sel:WORD_1
	v_or_b32_sdwa v66, v66, v74 dst_sel:DWORD dst_unused:UNUSED_PAD src0_sel:DWORD src1_sel:WORD_1
	ds_write_b64 v70, v[66:67] offset:528
	ds_read_b128 v[80:83], v88 offset:3072
	s_waitcnt lgkmcnt(0)
	v_mov_b32_e32 v66, v81
	v_mov_b32_e32 v67, v82
	v_mov_b32_e32 v84, v80
	v_mov_b32_e32 v85, v83
	v_pk_add_f32 v[66:67], v[66:67], v[84:85]
	s_nop 0
	v_add_f32_e32 v66, v66, v67
	s_waitcnt lgkmcnt(0)
	s_nop 1
	v_add_f32_dpp v66, v66, v66 quad_perm:[1,0,3,2] row_mask:0xf bank_mask:0xf
	s_waitcnt lgkmcnt(0)
	s_nop 1
	v_add_f32_dpp v66, v66, v66 quad_perm:[2,3,0,1] row_mask:0xf bank_mask:0xf
	s_waitcnt lgkmcnt(0)
	s_nop 1
	v_add_f32_dpp v66, v66, v66 row_half_mirror row_mask:0xf bank_mask:0xf
	s_waitcnt lgkmcnt(0)
	s_nop 1
	v_add_f32_dpp v66, v66, v66 row_mirror row_mask:0xf bank_mask:0xf
	s_waitcnt lgkmcnt(0)
	v_mov_b32_e32 v67, v66
	v_mov_b32_e32 v254, v66
	s_nop 1
	v_permlane16_swap_b32 v67, v254
	v_add_f32_e32 v66, v67, v254
	s_waitcnt lgkmcnt(0)
	v_mov_b32_e32 v67, v66
	v_mov_b32_e32 v254, v66
	s_nop 1
	v_permlane32_swap_b32 v67, v254
	v_add_f32_e32 v71, v67, v254
	v_fmamk_f32 v67, v71, 0xbb800000, v81
	v_fmamk_f32 v66, v71, 0xbb800000, v80
	v_fmamk_f32 v83, v71, 0xbb800000, v83
	v_fmac_f32_e32 v82, 0xbb800000, v71
	v_pk_mul_f32 v[80:81], v[82:83], v[82:83]
	v_pk_mul_f32 v[84:85], v[66:67], v[66:67]
	s_nop 0
	v_pk_mov_b32 v[86:87], v[84:85], v[80:81] op_sel:[1,0]
	v_mov_b32_e32 v85, v81
	v_pk_add_f32 v[80:81], v[86:87], v[84:85]
	s_nop 0
	v_add_f32_e32 v71, v80, v81
	v_mov_b32_e32 v80, v66
	v_mov_b32_e32 v81, v82
	v_mov_b32_e32 v82, v67
	s_waitcnt lgkmcnt(0)
	s_nop 1
	v_add_f32_dpp v71, v71, v71 quad_perm:[1,0,3,2] row_mask:0xf bank_mask:0xf
	s_waitcnt lgkmcnt(0)
	s_nop 1
	v_add_f32_dpp v71, v71, v71 quad_perm:[2,3,0,1] row_mask:0xf bank_mask:0xf
	s_waitcnt lgkmcnt(0)
	s_nop 1
	v_add_f32_dpp v71, v71, v71 row_half_mirror row_mask:0xf bank_mask:0xf
	s_waitcnt lgkmcnt(0)
	s_nop 1
	v_add_f32_dpp v71, v71, v71 row_mirror row_mask:0xf bank_mask:0xf
	s_waitcnt lgkmcnt(0)
	v_mov_b32_e32 v74, v71
	v_mov_b32_e32 v254, v71
	s_nop 1
	v_permlane16_swap_b32 v74, v254
	v_add_f32_e32 v71, v74, v254
	s_waitcnt lgkmcnt(0)
	v_mov_b32_e32 v74, v71
	v_mov_b32_e32 v254, v71
	s_nop 1
	v_permlane32_swap_b32 v74, v254
	v_add_f32_e32 v71, v74, v254
	v_fmamk_f32 v71, v71, 0x3b800000, v111
	v_mul_f32_e32 v74, 0x4b800000, v71
	v_cmp_gt_f32_e32 vcc, s42, v71
	s_nop 1
	v_cndmask_b32_e32 v71, v71, v74, vcc
	v_rsq_f32_e32 v71, v71
	s_nop 0
	v_mul_f32_e32 v74, 0x45800000, v71
	v_cndmask_b32_e32 v74, v71, v74, vcc
	v_pk_mul_f32 v[80:81], v[80:81], v[74:75] op_sel_hi:[1,0]
	s_nop 0
	v_pk_fma_f32 v[76:77], v[76:77], v[80:81], v[78:79]
	s_nop 0
	v_mul_f32_e32 v66, 0xbfb8aa3b, v76
	v_exp_f32_e32 v71, v66
	v_pk_mul_f32 v[66:67], v[82:83], v[74:75] op_sel_hi:[1,0]
	v_and_b32_e32 v74, 15, v114
	v_pk_fma_f32 v[66:67], v[68:69], v[66:67], v[72:73]
	s_nop 0
	v_mul_f32_e32 v68, 0xbfb8aa3b, v66
	v_exp_f32_e32 v69, v68
	v_add_f32_e32 v68, 1.0, v71
	v_mul_f32_e32 v71, 0xbfb8aa3b, v77
	v_exp_f32_e32 v71, v71
	v_mul_f32_e32 v72, 0xbfb8aa3b, v67
	v_exp_f32_e32 v73, v72
	v_add_f32_e32 v69, 1.0, v69
	v_rcp_f32_e32 v72, v69
	v_add_f32_e32 v69, 1.0, v71
	v_rcp_f32_e32 v68, v68
	v_rcp_f32_e32 v69, v69
	v_add_f32_e32 v71, 1.0, v73
	v_rcp_f32_e32 v73, v71
	v_pk_mul_f32 v[68:69], v[76:77], v[68:69]
	s_nop 0
	v_and_b32_sdwa v71, v69, v112 dst_sel:DWORD dst_unused:UNUSED_PAD src0_sel:WORD_1 src1_sel:DWORD
	v_pk_mul_f32 v[66:67], v[66:67], v[72:73]
	v_and_b32_sdwa v72, v68, v112 dst_sel:DWORD dst_unused:UNUSED_PAD src0_sel:WORD_1 src1_sel:DWORD
	v_add3_u32 v68, v68, v72, s43
	v_add3_u32 v69, v69, v71, s43
	v_and_b32_sdwa v71, v67, v112 dst_sel:DWORD dst_unused:UNUSED_PAD src0_sel:WORD_1 src1_sel:DWORD
	v_and_b32_sdwa v72, v66, v112 dst_sel:DWORD dst_unused:UNUSED_PAD src0_sel:WORD_1 src1_sel:DWORD
	v_add3_u32 v67, v67, v71, s43
	v_add3_u32 v66, v66, v72, s43
	v_and_b32_e32 v67, 0xffff0000, v67
	v_and_b32_e32 v66, 0xffff0000, v66
	v_or_b32_sdwa v67, v67, v69 dst_sel:DWORD dst_unused:UNUSED_PAD src0_sel:DWORD src1_sel:WORD_1
	v_or_b32_sdwa v66, v66, v68 dst_sel:DWORD dst_unused:UNUSED_PAD src0_sel:DWORD src1_sel:WORD_1
	ds_write_b64 v70, v[66:67] offset:1056
	v_and_b32_e32 v66, 48, v114
	v_mul_u32_u24_e32 v67, 0x210, v74
	v_add3_u32 v100, s41, v66, v67
	s_waitcnt lgkmcnt(0)
	s_barrier
	ds_read_b128 v[66:69], v100
	ds_read_b128 v[70:73], v100 offset:64
	ds_read_b128 v[80:83], v100 offset:8448
	ds_read_b128 v[84:87], v100 offset:8512
	s_waitcnt lgkmcnt(3)
	v_mfma_f32_16x16x32_bf16 v[76:79], v[2:5], v[66:69], 0
	s_waitcnt lgkmcnt(1)
	v_mfma_f32_16x16x32_bf16 v[88:91], v[2:5], v[80:83], 0
	v_mfma_f32_16x16x32_bf16 v[66:69], v[34:37], v[66:69], 0
	v_mfma_f32_16x16x32_bf16 v[80:83], v[34:37], v[80:83], 0
	v_mfma_f32_16x16x32_bf16 v[76:79], v[6:9], v[70:73], v[76:79]
	s_waitcnt lgkmcnt(0)
	v_mfma_f32_16x16x32_bf16 v[88:91], v[6:9], v[84:87], v[88:91]
	v_mfma_f32_16x16x32_bf16 v[66:69], v[38:41], v[70:73], v[66:69]
	v_mfma_f32_16x16x32_bf16 v[70:73], v[38:41], v[84:87], v[80:83]
	s_nop 2
	ds_read_b128 v[80:83], v100 offset:128
	ds_read_b128 v[84:87], v100 offset:192
	ds_read_b128 v[92:95], v100 offset:8576
	ds_read_b128 v[96:99], v100 offset:8640
	s_waitcnt lgkmcnt(3)
	v_mfma_f32_16x16x32_bf16 v[76:79], v[10:13], v[80:83], v[76:79]
	s_waitcnt lgkmcnt(1)
	v_mfma_f32_16x16x32_bf16 v[88:91], v[10:13], v[92:95], v[88:91]
	v_mfma_f32_16x16x32_bf16 v[66:69], v[42:45], v[80:83], v[66:69]
	v_mfma_f32_16x16x32_bf16 v[70:73], v[42:45], v[92:95], v[70:73]
	v_mfma_f32_16x16x32_bf16 v[76:79], v[14:17], v[84:87], v[76:79]
	s_waitcnt lgkmcnt(0)
	v_mfma_f32_16x16x32_bf16 v[80:83], v[14:17], v[96:99], v[88:91]
	v_mfma_f32_16x16x32_bf16 v[66:69], v[46:49], v[84:87], v[66:69]
	ds_read_b128 v[84:87], v100 offset:256
	s_nop 0
	ds_read_b128 v[88:91], v100 offset:320
	v_mfma_f32_16x16x32_bf16 v[70:73], v[46:49], v[96:99], v[70:73]
	ds_read_b128 v[92:95], v100 offset:8704
	ds_read_b128 v[96:99], v100 offset:8768
	s_waitcnt lgkmcnt(3)
	v_mfma_f32_16x16x32_bf16 v[76:79], v[18:21], v[84:87], v[76:79]
	v_mfma_f32_16x16x32_bf16 v[66:69], v[50:53], v[84:87], v[66:69]
	s_waitcnt lgkmcnt(1)
	v_mfma_f32_16x16x32_bf16 v[80:83], v[18:21], v[92:95], v[80:83]
	v_mfma_f32_16x16x32_bf16 v[70:73], v[50:53], v[92:95], v[70:73]
	v_mfma_f32_16x16x32_bf16 v[76:79], v[22:25], v[88:91], v[76:79]
	v_mfma_f32_16x16x32_bf16 v[66:69], v[54:57], v[88:91], v[66:69]
	ds_read_b128 v[84:87], v100 offset:384
	ds_read_b128 v[88:91], v100 offset:448
	s_waitcnt lgkmcnt(2)
	v_mfma_f32_16x16x32_bf16 v[80:83], v[22:25], v[96:99], v[80:83]
	v_mfma_f32_16x16x32_bf16 v[70:73], v[54:57], v[96:99], v[70:73]
	ds_read_b128 v[92:95], v100 offset:8832
	ds_read_b128 v[96:99], v100 offset:8896
	s_waitcnt lgkmcnt(3)
	v_mfma_f32_16x16x32_bf16 v[76:79], v[26:29], v[84:87], v[76:79]
	v_mfma_f32_16x16x32_bf16 v[66:69], v[58:61], v[84:87], v[66:69]
	v_lshrrev_b32_e32 v84, 2, v114
	v_and_b32_e32 v84, 12, v84
	s_waitcnt lgkmcnt(1)
	v_mfma_f32_16x16x32_bf16 v[80:83], v[26:29], v[92:95], v[80:83]
	v_mfma_f32_16x16x32_bf16 v[70:73], v[58:61], v[92:95], v[70:73]
	v_lshl_or_b32 v92, v113, 5, v84
	v_ashrrev_i32_e32 v93, 31, v92
	v_lshl_add_u64 v[94:95], v[92:93], 2, s[10:11]
	global_load_dwordx4 v[84:87], v[94:95], off offset:1024
	v_mfma_f32_16x16x32_bf16 v[76:79], v[30:33], v[88:91], v[76:79]
	v_mfma_f32_16x16x32_bf16 v[66:69], v[62:65], v[88:91], v[66:69]
	v_add_u32_e32 v88, s3, v74
	s_add_i32 s3, s3, s28
	s_cmpk_lt_i32 s46, 0x400
	s_waitcnt lgkmcnt(0)
	v_mfma_f32_16x16x32_bf16 v[80:83], v[30:33], v[96:99], v[80:83]
	s_waitcnt vmcnt(0)
	s_nop 0
	v_pk_add_f32 v[78:79], v[78:79], v[86:87]
	v_pk_add_f32 v[76:77], v[76:77], v[84:85]
	v_and_b32_sdwa v74, v78, v112 dst_sel:DWORD dst_unused:UNUSED_PAD src0_sel:WORD_1 src1_sel:DWORD
	v_and_b32_sdwa v89, v76, v112 dst_sel:DWORD dst_unused:UNUSED_PAD src0_sel:WORD_1 src1_sel:DWORD
	v_add3_u32 v76, v76, v89, s43
	v_add3_u32 v74, v78, v74, s43
	v_and_b32_sdwa v78, v79, v112 dst_sel:DWORD dst_unused:UNUSED_PAD src0_sel:WORD_1 src1_sel:DWORD
	v_and_b32_sdwa v89, v77, v112 dst_sel:DWORD dst_unused:UNUSED_PAD src0_sel:WORD_1 src1_sel:DWORD
	v_add3_u32 v78, v79, v78, s43
	v_add3_u32 v77, v77, v89, s43
	v_and_b32_e32 v78, 0xffff0000, v78
	v_and_b32_e32 v79, 0xffff0000, v77
	v_ashrrev_i32_e32 v89, 31, v88
	v_or_b32_sdwa v77, v78, v74 dst_sel:DWORD dst_unused:UNUSED_PAD src0_sel:DWORD src1_sel:WORD_1
	v_or_b32_sdwa v76, v79, v76 dst_sel:DWORD dst_unused:UNUSED_PAD src0_sel:DWORD src1_sel:WORD_1
	v_lshlrev_b64 v[78:79], 11, v[88:89]
	v_lshl_add_u64 v[78:79], s[88:89], 0, v[78:79]
	v_lshl_add_u64 v[90:91], v[78:79], 0, s[24:25]
	v_lshlrev_b64 v[78:79], 1, v[92:93]
	v_lshl_add_u64 v[100:101], v[90:91], 0, v[78:79]
	v_pk_add_f32 v[82:83], v[82:83], v[86:87]
	v_pk_add_f32 v[80:81], v[80:81], v[84:85]
	global_store_dwordx2 v[100:101], v[76:77], off
	v_and_b32_sdwa v74, v82, v112 dst_sel:DWORD dst_unused:UNUSED_PAD src0_sel:WORD_1 src1_sel:DWORD
	v_and_b32_sdwa v77, v80, v112 dst_sel:DWORD dst_unused:UNUSED_PAD src0_sel:WORD_1 src1_sel:DWORD
	v_add3_u32 v77, v80, v77, s43
	v_add3_u32 v74, v82, v74, s43
	v_and_b32_sdwa v80, v83, v112 dst_sel:DWORD dst_unused:UNUSED_PAD src0_sel:WORD_1 src1_sel:DWORD
	v_and_b32_sdwa v82, v81, v112 dst_sel:DWORD dst_unused:UNUSED_PAD src0_sel:WORD_1 src1_sel:DWORD
	v_add3_u32 v80, v83, v80, s43
	v_add3_u32 v81, v81, v82, s43
	v_add_u32_e32 v76, 16, v88
	v_and_b32_e32 v80, 0xffff0000, v80
	v_and_b32_e32 v82, 0xffff0000, v81
	v_or_b32_sdwa v81, v80, v74 dst_sel:DWORD dst_unused:UNUSED_PAD src0_sel:DWORD src1_sel:WORD_1
	v_or_b32_sdwa v80, v82, v77 dst_sel:DWORD dst_unused:UNUSED_PAD src0_sel:DWORD src1_sel:WORD_1
	v_ashrrev_i32_e32 v77, 31, v76
	v_lshlrev_b64 v[76:77], 11, v[76:77]
	v_lshl_add_u64 v[76:77], s[88:89], 0, v[76:77]
	v_lshl_add_u64 v[82:83], v[76:77], 0, s[24:25]
	v_lshl_add_u64 v[76:77], v[82:83], 0, v[78:79]
	global_store_dwordx2 v[76:77], v[80:81], off
	global_load_dwordx4 v[76:79], v[94:95], off offset:1088
	v_mfma_f32_16x16x32_bf16 v[70:73], v[62:65], v[96:99], v[70:73]
	v_or_b32_e32 v80, 16, v92
	v_ashrrev_i32_e32 v81, 31, v80
	s_waitcnt vmcnt(0)
	v_pk_add_f32 v[68:69], v[68:69], v[78:79]
	v_pk_add_f32 v[66:67], v[66:67], v[76:77]
	v_and_b32_sdwa v74, v68, v112 dst_sel:DWORD dst_unused:UNUSED_PAD src0_sel:WORD_1 src1_sel:DWORD
	v_and_b32_sdwa v84, v66, v112 dst_sel:DWORD dst_unused:UNUSED_PAD src0_sel:WORD_1 src1_sel:DWORD
	v_add3_u32 v68, v68, v74, s43
	v_and_b32_sdwa v74, v69, v112 dst_sel:DWORD dst_unused:UNUSED_PAD src0_sel:WORD_1 src1_sel:DWORD
	v_add3_u32 v66, v66, v84, s43
	v_and_b32_sdwa v84, v67, v112 dst_sel:DWORD dst_unused:UNUSED_PAD src0_sel:WORD_1 src1_sel:DWORD
	v_add3_u32 v69, v69, v74, s43
	v_add3_u32 v67, v67, v84, s43
	v_and_b32_e32 v69, 0xffff0000, v69
	v_and_b32_e32 v74, 0xffff0000, v67
	v_or_b32_sdwa v67, v69, v68 dst_sel:DWORD dst_unused:UNUSED_PAD src0_sel:DWORD src1_sel:WORD_1
	v_lshlrev_b64 v[68:69], 1, v[80:81]
	v_or_b32_sdwa v66, v74, v66 dst_sel:DWORD dst_unused:UNUSED_PAD src0_sel:DWORD src1_sel:WORD_1
	v_lshl_add_u64 v[80:81], v[90:91], 0, v[68:69]
	global_store_dwordx2 v[80:81], v[66:67], off
	v_pk_add_f32 v[66:67], v[72:73], v[78:79]
	v_pk_add_f32 v[70:71], v[70:71], v[76:77]
	v_and_b32_sdwa v72, v66, v112 dst_sel:DWORD dst_unused:UNUSED_PAD src0_sel:WORD_1 src1_sel:DWORD
	v_and_b32_sdwa v73, v70, v112 dst_sel:DWORD dst_unused:UNUSED_PAD src0_sel:WORD_1 src1_sel:DWORD
	v_add3_u32 v70, v70, v73, s43
	v_add3_u32 v66, v66, v72, s43
	v_and_b32_sdwa v72, v67, v112 dst_sel:DWORD dst_unused:UNUSED_PAD src0_sel:WORD_1 src1_sel:DWORD
	v_and_b32_sdwa v73, v71, v112 dst_sel:DWORD dst_unused:UNUSED_PAD src0_sel:WORD_1 src1_sel:DWORD
	v_add3_u32 v67, v67, v72, s43
	v_add3_u32 v71, v71, v73, s43
	v_and_b32_e32 v67, 0xffff0000, v67
	v_and_b32_e32 v71, 0xffff0000, v71
	v_or_b32_sdwa v67, v67, v66 dst_sel:DWORD dst_unused:UNUSED_PAD src0_sel:DWORD src1_sel:WORD_1
	v_or_b32_sdwa v66, v71, v70 dst_sel:DWORD dst_unused:UNUSED_PAD src0_sel:DWORD src1_sel:WORD_1
	v_lshl_add_u64 v[68:69], v[82:83], 0, v[68:69]
	global_store_dwordx2 v[68:69], v[66:67], off
	s_barrier
	s_cbranch_scc0 .LBB0_1997
